# c22 + P8 gate epilogue VALU trim: canonicalising v_max dropped in front of the -60 clamp (128), alignbit+and unpack folded to one shift (64); bit-identical
# baseline (speedup 1.0000x reference)
; __device__ __forceinline__ unsigned cvt_pk_bf16(float lo, float hi) { unsigned r; asm volatile("v_cvt_pk_bf16_f32 %0, %1, %2" : "=v"(r) : "v"(lo), "v"(hi)); return r; }
;     __device__ __forceinline__ void operator()(f32x4 (&acc)[2][2][4][2], const Unit& u, int wr, int wc, int fr, int fq) const {
;     ...
;                         const unsigned long long wb = wbv[m][bj][n];
;                         f32x4 eb;
;                         eb[0] = __expf(-fmaxf(__uint_as_float((unsigned)(wb & 0xffffull) << 16), -60.f)); eb[1] = __expf(-fmaxf(__uint_as_float((unsigned)((wb >> 16) & 0xffffull) << 16), -60.f));
;                         eb[2] = __expf(-fmaxf(__uint_as_float((unsigned)((wb >> 32) & 0xffffull) << 16), -60.f)); eb[3] = __expf(-fmaxf(__uint_as_float((unsigned)((wb >> 48) & 0xffffull) << 16), -60.f));
;                         if (u.kh == 0) {
;                             const unsigned long long wa = wav[m][bj][n];
;                             f32x4 ea;
;                             ea[0] = __expf(-__uint_as_float((unsigned)(wa & 0xffffull) << 16)); ea[1] = __expf(-__uint_as_float((unsigned)((wa >> 16) & 0xffffull) << 16));
;                             ea[2] = __expf(-__uint_as_float((unsigned)((wa >> 32) & 0xffffull) << 16)); ea[3] = __expf(-__uint_as_float((unsigned)((wa >> 48) & 0xffffull) << 16));
; #pragma unroll
;                             for (int e_ = 0; e_ < 4; ++e_) acc[ai][bj][m][n][e_] *= (1.0f + eb[e_]) * __builtin_amdgcn_rcpf(1.0f + ea[e_]);
;                         } else {
;                             f32x4 o;
; #pragma unroll
;                             for (int e_ = 0; e_ < 4; ++e_) o[e_] = acc[ai][bj][m][n][e_] * __builtin_amdgcn_rcpf(1.0f + eb[e_]);
;                             *(unsigned long long*)(merged + off + bj * HALF + 16 * n) = (unsigned long long)cvt_pk_bf16(o[0], o[1]) | ((unsigned long long)cvt_pk_bf16(o[2], o[3]) << 32);
;                         } } }
.LBB0_931:
	s_waitcnt vmcnt(0)
	v_lshlrev_b32_e32 v1, 16, v212
	v_max_f32_e32 v1, 0xc2700000, v1
	v_mul_f32_e32 v1, 0xbfb8aa3b, v1
	v_exp_f32_e32 v218, v1
	v_and_b32_e32 v1, 0xffff0000, v212
	v_max_f32_e32 v1, 0xc2700000, v1
	v_mul_f32_e32 v1, 0xbfb8aa3b, v1
	v_exp_f32_e32 v219, v1
	v_lshlrev_b32_e32 v1, 16, v213
	v_max_f32_e32 v1, 0xc2700000, v1
	v_mul_f32_e32 v1, 0xbfb8aa3b, v1
	v_exp_f32_e32 v220, v1
	v_and_b32_e32 v1, 0xffff0000, v213
	v_max_f32_e32 v1, 0xc2700000, v1
	v_mul_f32_e32 v1, 0xbfb8aa3b, v1
	v_exp_f32_e32 v221, v1
	v_or_b32_e32 v2, s21, v225
	v_lshlrev_b64 v[228:229], 11, v[144:145]
	v_ashrrev_i32_e32 v3, 31, v2
	v_cndmask_b32_e64 v1, 0, 1, s[38:39]
	v_lshl_add_u64 v[212:213], s[14:15], 0, v[228:229]
	s_mov_b64 s[42:43], -1
	v_cmp_ne_u32_e64 s[4:5], 1, v1
	s_andn2_b64 vcc, exec, s[38:39]
	v_lshl_add_u64 v[212:213], v[2:3], 1, v[212:213]
	s_cbranch_vccnz .LBB0_933
	v_add_f32_e32 v1, 1.0, v218
	v_add_f32_e32 v145, 1.0, v219
	v_add_f32_e32 v222, 1.0, v220
	v_add_f32_e32 v227, 1.0, v221
	v_rcp_f32_e32 v1, v1
	v_rcp_f32_e32 v145, v145
	v_rcp_f32_e32 v222, v222
	v_rcp_f32_e32 v227, v227
	s_mov_b64 s[42:43], 0
	v_mul_f32_e32 v1, v128, v1
	v_mul_f32_e32 v145, v129, v145
	v_mul_f32_e32 v222, v130, v222
	v_mul_f32_e32 v227, v131, v227
	v_cvt_pk_bf16_f32 v228, v1, v145
	v_cvt_pk_bf16_f32 v229, v222, v227
	global_store_dwordx2 v[212:213], v[228:229], off
.LBB0_933:
	s_andn2_b64 vcc, exec, s[42:43]
	s_cbranch_vccnz .LBB0_935
	v_lshlrev_b32_e32 v1, 16, v216
	v_and_b32_e32 v145, 0xffff0000, v216
	v_lshlrev_b32_e32 v216, 16, v217
	v_mul_f32_e32 v1, 0xbfb8aa3b, v1
	v_mul_f32_e32 v216, 0xbfb8aa3b, v216
	v_exp_f32_e32 v1, v1
	v_mul_f32_e32 v145, 0xbfb8aa3b, v145
	v_exp_f32_e32 v222, v216
	v_and_b32_e32 v216, 0xffff0000, v217
	v_exp_f32_e32 v145, v145
	v_mul_f32_e32 v216, 0xbfb8aa3b, v216
	v_exp_f32_e32 v217, v216
	v_add_f32_e32 v1, 1.0, v1
	v_rcp_f32_e32 v216, v1
	v_add_f32_e32 v1, 1.0, v145
	v_add_f32_e32 v145, 1.0, v222
	v_rcp_f32_e32 v228, v145
	v_add_f32_e32 v145, 1.0, v217
	v_rcp_f32_e32 v229, v145
	v_rcp_f32_e32 v217, v1
	v_pk_add_f32 v[218:219], v[218:219], 1.0 op_sel_hi:[1,0]
	v_pk_add_f32 v[220:221], v[220:221], 1.0 op_sel_hi:[1,0]
	v_pk_mul_f32 v[216:217], v[218:219], v[216:217]
	v_pk_mul_f32 v[220:221], v[220:221], v[228:229]
	v_pk_mul_f32 v[128:129], v[128:129], v[216:217]
	v_pk_mul_f32 v[130:131], v[130:131], v[220:221]
.LBB0_935:
	v_lshlrev_b32_e32 v1, 16, v214
	v_max_f32_e32 v1, 0xc2700000, v1
	v_mul_f32_e32 v1, 0xbfb8aa3b, v1
	v_exp_f32_e32 v216, v1
	v_and_b32_e32 v1, 0xffff0000, v214
	v_max_f32_e32 v1, 0xc2700000, v1
	v_mul_f32_e32 v1, 0xbfb8aa3b, v1
	v_exp_f32_e32 v217, v1
	v_lshlrev_b32_e32 v1, 16, v215
	v_max_f32_e32 v1, 0xc2700000, v1
	v_mul_f32_e32 v1, 0xbfb8aa3b, v1
	v_exp_f32_e32 v214, v1
	v_and_b32_e32 v1, 0xffff0000, v215
	v_max_f32_e32 v1, 0xc2700000, v1
	v_mul_f32_e32 v1, 0xbfb8aa3b, v1
	v_exp_f32_e32 v215, v1
	s_and_b64 vcc, exec, s[4:5]
	s_mov_b64 s[38:39], -1
	s_cbranch_vccnz .LBB0_937
	v_add_f32_e32 v219, 1.0, v215
	v_add_f32_e32 v1, 1.0, v216
	v_add_f32_e32 v145, 1.0, v217
	v_add_f32_e32 v218, 1.0, v214
	v_rcp_f32_e32 v219, v219
	v_rcp_f32_e32 v1, v1
	v_rcp_f32_e32 v145, v145
	v_rcp_f32_e32 v218, v218
	v_mul_f32_e32 v219, v127, v219
	s_mov_b64 s[38:39], 0
	v_mul_f32_e32 v1, v124, v1
	v_mul_f32_e32 v145, v125, v145
	v_mul_f32_e32 v220, v126, v218
	v_cvt_pk_bf16_f32 v218, v1, v145
	v_cvt_pk_bf16_f32 v219, v220, v219
	global_store_dwordx2 v[212:213], v[218:219], off offset:32
.LBB0_937:
	s_andn2_b64 vcc, exec, s[38:39]
	s_cbranch_vccnz .LBB0_939
	v_lshlrev_b32_e32 v1, 16, v210
	v_and_b32_e32 v145, 0xffff0000, v210
	v_lshlrev_b32_e32 v210, 16, v211
	v_mul_f32_e32 v1, 0xbfb8aa3b, v1
	v_mul_f32_e32 v210, 0xbfb8aa3b, v210
	v_exp_f32_e32 v1, v1
	v_mul_f32_e32 v145, 0xbfb8aa3b, v145
	v_exp_f32_e32 v218, v210
	v_and_b32_e32 v210, 0xffff0000, v211
	v_exp_f32_e32 v145, v145
	v_mul_f32_e32 v210, 0xbfb8aa3b, v210
	v_exp_f32_e32 v211, v210
	v_add_f32_e32 v1, 1.0, v1
	v_rcp_f32_e32 v210, v1
	v_add_f32_e32 v1, 1.0, v145
	v_add_f32_e32 v145, 1.0, v218
	v_rcp_f32_e32 v218, v145
	v_add_f32_e32 v145, 1.0, v211
	v_rcp_f32_e32 v219, v145
	v_rcp_f32_e32 v211, v1
	v_pk_add_f32 v[216:217], v[216:217], 1.0 op_sel_hi:[1,0]
	v_pk_add_f32 v[214:215], v[214:215], 1.0 op_sel_hi:[1,0]
	v_pk_mul_f32 v[210:211], v[216:217], v[210:211]
	v_pk_mul_f32 v[214:215], v[214:215], v[218:219]
	v_pk_mul_f32 v[124:125], v[124:125], v[210:211]
	v_pk_mul_f32 v[126:127], v[126:127], v[214:215]
.LBB0_939:
	v_lshlrev_b32_e32 v1, 16, v208
	v_max_f32_e32 v1, 0xc2700000, v1
	v_mul_f32_e32 v1, 0xbfb8aa3b, v1
	v_exp_f32_e32 v210, v1
	v_and_b32_e32 v1, 0xffff0000, v208
	v_max_f32_e32 v1, 0xc2700000, v1
	v_mul_f32_e32 v1, 0xbfb8aa3b, v1
	v_exp_f32_e32 v211, v1
	v_lshlrev_b32_e32 v1, 16, v209
	v_max_f32_e32 v1, 0xc2700000, v1
	v_mul_f32_e32 v1, 0xbfb8aa3b, v1
	v_exp_f32_e32 v208, v1
	v_and_b32_e32 v1, 0xffff0000, v209
	v_max_f32_e32 v1, 0xc2700000, v1
	v_mul_f32_e32 v1, 0xbfb8aa3b, v1
	v_exp_f32_e32 v209, v1
	s_and_b64 vcc, exec, s[4:5]
	s_mov_b64 s[38:39], -1
	s_cbranch_vccnz .LBB0_941
	v_add_f32_e32 v215, 1.0, v209
	v_add_f32_e32 v1, 1.0, v210
	v_add_f32_e32 v145, 1.0, v211
	v_add_f32_e32 v214, 1.0, v208
	v_rcp_f32_e32 v215, v215
	v_rcp_f32_e32 v1, v1
	v_rcp_f32_e32 v145, v145
	v_rcp_f32_e32 v214, v214
	v_mul_f32_e32 v215, v99, v215
	s_mov_b64 s[38:39], 0
	v_mul_f32_e32 v1, v96, v1
	v_mul_f32_e32 v145, v97, v145
	v_mul_f32_e32 v216, v98, v214
	v_cvt_pk_bf16_f32 v214, v1, v145
	v_cvt_pk_bf16_f32 v215, v216, v215
	global_store_dwordx2 v[212:213], v[214:215], off offset:256
; __device__ __forceinline__ unsigned cvt_pk_bf16(float lo, float hi) { unsigned r; asm volatile("v_cvt_pk_bf16_f32 %0, %1, %2" : "=v"(r) : "v"(lo), "v"(hi)); return r; }
;     __device__ __forceinline__ void operator()(f32x4 (&acc)[2][2][4][2], const Unit& u, int wr, int wc, int fr, int fq) const {
;     ...
;                         const unsigned long long wb = wbv[m][bj][n];
;                         f32x4 eb;
;                         eb[0] = __expf(-fmaxf(__uint_as_float((unsigned)(wb & 0xffffull) << 16), -60.f)); eb[1] = __expf(-fmaxf(__uint_as_float((unsigned)((wb >> 16) & 0xffffull) << 16), -60.f));
;                         eb[2] = __expf(-fmaxf(__uint_as_float((unsigned)((wb >> 32) & 0xffffull) << 16), -60.f)); eb[3] = __expf(-fmaxf(__uint_as_float((unsigned)((wb >> 48) & 0xffffull) << 16), -60.f));
;                         if (u.kh == 0) {
;                             const unsigned long long wa = wav[m][bj][n];
;                             f32x4 ea;
;                             ea[0] = __expf(-__uint_as_float((unsigned)(wa & 0xffffull) << 16)); ea[1] = __expf(-__uint_as_float((unsigned)((wa >> 16) & 0xffffull) << 16));
;                             ea[2] = __expf(-__uint_as_float((unsigned)((wa >> 32) & 0xffffull) << 16)); ea[3] = __expf(-__uint_as_float((unsigned)((wa >> 48) & 0xffffull) << 16));
; #pragma unroll
;                             for (int e_ = 0; e_ < 4; ++e_) acc[ai][bj][m][n][e_] *= (1.0f + eb[e_]) * __builtin_amdgcn_rcpf(1.0f + ea[e_]);
;                         } else {
;                             f32x4 o;
; #pragma unroll
;                             for (int e_ = 0; e_ < 4; ++e_) o[e_] = acc[ai][bj][m][n][e_] * __builtin_amdgcn_rcpf(1.0f + eb[e_]);
;                             *(unsigned long long*)(merged + off + bj * HALF + 16 * n) = (unsigned long long)cvt_pk_bf16(o[0], o[1]) | ((unsigned long long)cvt_pk_bf16(o[2], o[3]) << 32);
;                         } } }
.LBB0_941:
	s_andn2_b64 vcc, exec, s[38:39]
	s_cbranch_vccnz .LBB0_943
	v_lshlrev_b32_e32 v1, 16, v206
	v_and_b32_e32 v145, 0xffff0000, v206
	v_lshlrev_b32_e32 v206, 16, v207
	v_mul_f32_e32 v1, 0xbfb8aa3b, v1
	v_mul_f32_e32 v206, 0xbfb8aa3b, v206
	v_exp_f32_e32 v1, v1
	v_mul_f32_e32 v145, 0xbfb8aa3b, v145
	v_exp_f32_e32 v214, v206
	v_and_b32_e32 v206, 0xffff0000, v207
	v_exp_f32_e32 v145, v145
	v_mul_f32_e32 v206, 0xbfb8aa3b, v206
	v_exp_f32_e32 v207, v206
	v_add_f32_e32 v1, 1.0, v1
	v_rcp_f32_e32 v206, v1
	v_add_f32_e32 v1, 1.0, v145
	v_add_f32_e32 v145, 1.0, v214
	v_rcp_f32_e32 v214, v145
	v_add_f32_e32 v145, 1.0, v207
	v_rcp_f32_e32 v215, v145
	v_rcp_f32_e32 v207, v1
	v_pk_add_f32 v[210:211], v[210:211], 1.0 op_sel_hi:[1,0]
	v_pk_add_f32 v[208:209], v[208:209], 1.0 op_sel_hi:[1,0]
	v_pk_mul_f32 v[206:207], v[210:211], v[206:207]
	v_pk_mul_f32 v[208:209], v[208:209], v[214:215]
	v_pk_mul_f32 v[96:97], v[96:97], v[206:207]
	v_pk_mul_f32 v[98:99], v[98:99], v[208:209]
.LBB0_943:
	v_lshlrev_b32_e32 v1, 16, v204
	v_max_f32_e32 v1, 0xc2700000, v1
	v_mul_f32_e32 v1, 0xbfb8aa3b, v1
	v_exp_f32_e32 v206, v1
	v_and_b32_e32 v1, 0xffff0000, v204
	v_max_f32_e32 v1, 0xc2700000, v1
	v_mul_f32_e32 v1, 0xbfb8aa3b, v1
	v_exp_f32_e32 v207, v1
	v_lshlrev_b32_e32 v1, 16, v205
	v_max_f32_e32 v1, 0xc2700000, v1
	v_mul_f32_e32 v1, 0xbfb8aa3b, v1
	v_exp_f32_e32 v204, v1
	v_and_b32_e32 v1, 0xffff0000, v205
	v_max_f32_e32 v1, 0xc2700000, v1
	v_mul_f32_e32 v1, 0xbfb8aa3b, v1
	v_exp_f32_e32 v205, v1
	s_and_b64 vcc, exec, s[4:5]
	s_mov_b64 s[38:39], -1
	s_cbranch_vccnz .LBB0_945
	v_add_f32_e32 v209, 1.0, v205
	v_add_f32_e32 v1, 1.0, v206
	v_add_f32_e32 v145, 1.0, v207
	v_add_f32_e32 v208, 1.0, v204
	v_rcp_f32_e32 v209, v209
	v_rcp_f32_e32 v1, v1
	v_rcp_f32_e32 v145, v145
	v_rcp_f32_e32 v208, v208
	v_mul_f32_e32 v209, v95, v209
	s_mov_b64 s[38:39], 0
	v_mul_f32_e32 v1, v92, v1
	v_mul_f32_e32 v145, v93, v145
	v_mul_f32_e32 v210, v94, v208
	v_cvt_pk_bf16_f32 v208, v1, v145
	v_cvt_pk_bf16_f32 v209, v210, v209
	global_store_dwordx2 v[212:213], v[208:209], off offset:288
.LBB0_945:
	s_andn2_b64 vcc, exec, s[38:39]
	s_cbranch_vccnz .LBB0_947
	v_lshlrev_b32_e32 v1, 16, v202
	v_and_b32_e32 v145, 0xffff0000, v202
	v_lshlrev_b32_e32 v202, 16, v203
	v_mul_f32_e32 v1, 0xbfb8aa3b, v1
	v_mul_f32_e32 v202, 0xbfb8aa3b, v202
	v_exp_f32_e32 v1, v1
	v_mul_f32_e32 v145, 0xbfb8aa3b, v145
	v_exp_f32_e32 v208, v202
	v_and_b32_e32 v202, 0xffff0000, v203
	v_exp_f32_e32 v145, v145
	v_mul_f32_e32 v202, 0xbfb8aa3b, v202
	v_exp_f32_e32 v203, v202
	v_add_f32_e32 v1, 1.0, v1
	v_rcp_f32_e32 v202, v1
	v_add_f32_e32 v1, 1.0, v145
	v_add_f32_e32 v145, 1.0, v208
	v_rcp_f32_e32 v208, v145
	v_add_f32_e32 v145, 1.0, v203
	v_rcp_f32_e32 v209, v145
	v_rcp_f32_e32 v203, v1
	v_pk_add_f32 v[206:207], v[206:207], 1.0 op_sel_hi:[1,0]
	v_pk_add_f32 v[204:205], v[204:205], 1.0 op_sel_hi:[1,0]
	v_pk_mul_f32 v[202:203], v[206:207], v[202:203]
	v_pk_mul_f32 v[204:205], v[204:205], v[208:209]
	v_pk_mul_f32 v[92:93], v[92:93], v[202:203]
	v_pk_mul_f32 v[94:95], v[94:95], v[204:205]
.LBB0_947:
	v_lshlrev_b32_e32 v1, 16, v198
	v_max_f32_e32 v1, 0xc2700000, v1
	v_mul_f32_e32 v1, 0xbfb8aa3b, v1
	v_lshlrev_b64 v[204:205], 11, v[200:201]
	v_exp_f32_e32 v200, v1
	v_and_b32_e32 v1, 0xffff0000, v198
	v_max_f32_e32 v1, 0xc2700000, v1
	v_mul_f32_e32 v1, 0xbfb8aa3b, v1
	v_exp_f32_e32 v201, v1
	v_lshlrev_b32_e32 v1, 16, v199
	v_max_f32_e32 v1, 0xc2700000, v1
	v_mul_f32_e32 v1, 0xbfb8aa3b, v1
	v_exp_f32_e32 v202, v1
	v_and_b32_e32 v1, 0xffff0000, v199
	v_max_f32_e32 v1, 0xc2700000, v1
	v_mul_f32_e32 v1, 0xbfb8aa3b, v1
	v_exp_f32_e32 v203, v1
	v_lshl_add_u64 v[198:199], s[14:15], 0, v[204:205]
	s_mov_b64 s[38:39], -1
	s_and_b64 vcc, exec, s[4:5]
	v_lshl_add_u64 v[198:199], v[2:3], 1, v[198:199]
	s_cbranch_vccnz .LBB0_949
	v_add_f32_e32 v205, 1.0, v203
	v_add_f32_e32 v1, 1.0, v200
	v_add_f32_e32 v145, 1.0, v201
	v_add_f32_e32 v204, 1.0, v202
	v_rcp_f32_e32 v205, v205
	v_rcp_f32_e32 v1, v1
	v_rcp_f32_e32 v145, v145
	v_rcp_f32_e32 v204, v204
	v_mul_f32_e32 v205, v123, v205
	s_mov_b64 s[38:39], 0
	v_mul_f32_e32 v1, v120, v1
	v_mul_f32_e32 v145, v121, v145
	v_mul_f32_e32 v206, v122, v204
	v_cvt_pk_bf16_f32 v204, v1, v145
	v_cvt_pk_bf16_f32 v205, v206, v205
	global_store_dwordx2 v[198:199], v[204:205], off
.LBB0_949:
	s_andn2_b64 vcc, exec, s[38:39]
	s_cbranch_vccnz .LBB0_951
	v_lshlrev_b32_e32 v1, 16, v196
	v_and_b32_e32 v145, 0xffff0000, v196
	v_lshlrev_b32_e32 v196, 16, v197
	v_mul_f32_e32 v1, 0xbfb8aa3b, v1
	v_mul_f32_e32 v196, 0xbfb8aa3b, v196
	v_exp_f32_e32 v1, v1
	v_mul_f32_e32 v145, 0xbfb8aa3b, v145
	v_exp_f32_e32 v204, v196
	v_and_b32_e32 v196, 0xffff0000, v197
	v_exp_f32_e32 v145, v145
	v_mul_f32_e32 v196, 0xbfb8aa3b, v196
	v_exp_f32_e32 v197, v196
	v_add_f32_e32 v1, 1.0, v1
	v_rcp_f32_e32 v196, v1
	v_add_f32_e32 v1, 1.0, v145
	v_add_f32_e32 v145, 1.0, v204
	v_rcp_f32_e32 v204, v145
	v_add_f32_e32 v145, 1.0, v197
	v_rcp_f32_e32 v205, v145
	v_rcp_f32_e32 v197, v1
	v_pk_add_f32 v[200:201], v[200:201], 1.0 op_sel_hi:[1,0]
	v_pk_add_f32 v[202:203], v[202:203], 1.0 op_sel_hi:[1,0]
	v_pk_mul_f32 v[196:197], v[200:201], v[196:197]
	v_pk_mul_f32 v[202:203], v[202:203], v[204:205]
	v_pk_mul_f32 v[120:121], v[120:121], v[196:197]
	v_pk_mul_f32 v[122:123], v[122:123], v[202:203]
; __device__ __forceinline__ unsigned cvt_pk_bf16(float lo, float hi) { unsigned r; asm volatile("v_cvt_pk_bf16_f32 %0, %1, %2" : "=v"(r) : "v"(lo), "v"(hi)); return r; }
;     __device__ __forceinline__ void operator()(f32x4 (&acc)[2][2][4][2], const Unit& u, int wr, int wc, int fr, int fq) const {
;     ...
;                         const unsigned long long wb = wbv[m][bj][n];
;                         f32x4 eb;
;                         eb[0] = __expf(-fmaxf(__uint_as_float((unsigned)(wb & 0xffffull) << 16), -60.f)); eb[1] = __expf(-fmaxf(__uint_as_float((unsigned)((wb >> 16) & 0xffffull) << 16), -60.f));
;                         eb[2] = __expf(-fmaxf(__uint_as_float((unsigned)((wb >> 32) & 0xffffull) << 16), -60.f)); eb[3] = __expf(-fmaxf(__uint_as_float((unsigned)((wb >> 48) & 0xffffull) << 16), -60.f));
;                         if (u.kh == 0) {
;                             const unsigned long long wa = wav[m][bj][n];
;                             f32x4 ea;
;                             ea[0] = __expf(-__uint_as_float((unsigned)(wa & 0xffffull) << 16)); ea[1] = __expf(-__uint_as_float((unsigned)((wa >> 16) & 0xffffull) << 16));
;                             ea[2] = __expf(-__uint_as_float((unsigned)((wa >> 32) & 0xffffull) << 16)); ea[3] = __expf(-__uint_as_float((unsigned)((wa >> 48) & 0xffffull) << 16));
; #pragma unroll
;                             for (int e_ = 0; e_ < 4; ++e_) acc[ai][bj][m][n][e_] *= (1.0f + eb[e_]) * __builtin_amdgcn_rcpf(1.0f + ea[e_]);
;                         } else {
;                             f32x4 o;
; #pragma unroll
;                             for (int e_ = 0; e_ < 4; ++e_) o[e_] = acc[ai][bj][m][n][e_] * __builtin_amdgcn_rcpf(1.0f + eb[e_]);
;                             *(unsigned long long*)(merged + off + bj * HALF + 16 * n) = (unsigned long long)cvt_pk_bf16(o[0], o[1]) | ((unsigned long long)cvt_pk_bf16(o[2], o[3]) << 32);
;                         } } }
.LBB0_951:
	v_lshlrev_b32_e32 v1, 16, v194
	v_max_f32_e32 v1, 0xc2700000, v1
	v_mul_f32_e32 v1, 0xbfb8aa3b, v1
	v_exp_f32_e32 v196, v1
	v_and_b32_e32 v1, 0xffff0000, v194
	v_max_f32_e32 v1, 0xc2700000, v1
	v_mul_f32_e32 v1, 0xbfb8aa3b, v1
	v_exp_f32_e32 v197, v1
	v_lshlrev_b32_e32 v1, 16, v195
	v_max_f32_e32 v1, 0xc2700000, v1
	v_mul_f32_e32 v1, 0xbfb8aa3b, v1
	v_exp_f32_e32 v194, v1
	v_and_b32_e32 v1, 0xffff0000, v195
	v_max_f32_e32 v1, 0xc2700000, v1
	v_mul_f32_e32 v1, 0xbfb8aa3b, v1
	v_exp_f32_e32 v195, v1
	s_and_b64 vcc, exec, s[4:5]
	s_mov_b64 s[38:39], -1
	s_cbranch_vccnz .LBB0_953
	v_add_f32_e32 v201, 1.0, v195
	v_add_f32_e32 v1, 1.0, v196
	v_add_f32_e32 v145, 1.0, v197
	v_add_f32_e32 v200, 1.0, v194
	v_rcp_f32_e32 v201, v201
	v_rcp_f32_e32 v1, v1
	v_rcp_f32_e32 v145, v145
	v_rcp_f32_e32 v200, v200
	v_mul_f32_e32 v201, v119, v201
	s_mov_b64 s[38:39], 0
	v_mul_f32_e32 v1, v116, v1
	v_mul_f32_e32 v145, v117, v145
	v_mul_f32_e32 v202, v118, v200
	v_cvt_pk_bf16_f32 v200, v1, v145
	v_cvt_pk_bf16_f32 v201, v202, v201
	global_store_dwordx2 v[198:199], v[200:201], off offset:32
.LBB0_953:
	s_andn2_b64 vcc, exec, s[38:39]
	s_cbranch_vccnz .LBB0_955
	v_lshlrev_b32_e32 v1, 16, v192
	v_and_b32_e32 v145, 0xffff0000, v192
	v_lshlrev_b32_e32 v192, 16, v193
	v_mul_f32_e32 v1, 0xbfb8aa3b, v1
	v_mul_f32_e32 v192, 0xbfb8aa3b, v192
	v_exp_f32_e32 v1, v1
	v_mul_f32_e32 v145, 0xbfb8aa3b, v145
	v_exp_f32_e32 v200, v192
	v_and_b32_e32 v192, 0xffff0000, v193
	v_exp_f32_e32 v145, v145
	v_mul_f32_e32 v192, 0xbfb8aa3b, v192
	v_exp_f32_e32 v193, v192
	v_add_f32_e32 v1, 1.0, v1
	v_rcp_f32_e32 v192, v1
	v_add_f32_e32 v1, 1.0, v145
	v_add_f32_e32 v145, 1.0, v200
	v_rcp_f32_e32 v200, v145
	v_add_f32_e32 v145, 1.0, v193
	v_rcp_f32_e32 v201, v145
	v_rcp_f32_e32 v193, v1
	v_pk_add_f32 v[196:197], v[196:197], 1.0 op_sel_hi:[1,0]
	v_pk_add_f32 v[194:195], v[194:195], 1.0 op_sel_hi:[1,0]
	v_pk_mul_f32 v[192:193], v[196:197], v[192:193]
	v_pk_mul_f32 v[194:195], v[194:195], v[200:201]
	v_pk_mul_f32 v[116:117], v[116:117], v[192:193]
	v_pk_mul_f32 v[118:119], v[118:119], v[194:195]
.LBB0_955:
	v_lshlrev_b32_e32 v1, 16, v190
	v_max_f32_e32 v1, 0xc2700000, v1
	v_mul_f32_e32 v1, 0xbfb8aa3b, v1
	v_exp_f32_e32 v192, v1
	v_and_b32_e32 v1, 0xffff0000, v190
	v_max_f32_e32 v1, 0xc2700000, v1
	v_mul_f32_e32 v1, 0xbfb8aa3b, v1
	v_exp_f32_e32 v193, v1
	v_lshlrev_b32_e32 v1, 16, v191
	v_max_f32_e32 v1, 0xc2700000, v1
	v_mul_f32_e32 v1, 0xbfb8aa3b, v1
	v_exp_f32_e32 v190, v1
	v_and_b32_e32 v1, 0xffff0000, v191
	v_max_f32_e32 v1, 0xc2700000, v1
	v_mul_f32_e32 v1, 0xbfb8aa3b, v1
	v_exp_f32_e32 v191, v1
	s_and_b64 vcc, exec, s[4:5]
	s_mov_b64 s[38:39], -1
	s_cbranch_vccnz .LBB0_957
	v_add_f32_e32 v195, 1.0, v191
	v_add_f32_e32 v1, 1.0, v192
	v_add_f32_e32 v145, 1.0, v193
	v_add_f32_e32 v194, 1.0, v190
	v_rcp_f32_e32 v195, v195
	v_rcp_f32_e32 v1, v1
	v_rcp_f32_e32 v145, v145
	v_rcp_f32_e32 v194, v194
	v_mul_f32_e32 v195, v91, v195
	s_mov_b64 s[38:39], 0
	v_mul_f32_e32 v1, v88, v1
	v_mul_f32_e32 v145, v89, v145
	v_mul_f32_e32 v196, v90, v194
	v_cvt_pk_bf16_f32 v194, v1, v145
	v_cvt_pk_bf16_f32 v195, v196, v195
	global_store_dwordx2 v[198:199], v[194:195], off offset:256
.LBB0_957:
	s_andn2_b64 vcc, exec, s[38:39]
	s_cbranch_vccnz .LBB0_959
	v_lshlrev_b32_e32 v1, 16, v188
	v_and_b32_e32 v145, 0xffff0000, v188
	v_lshlrev_b32_e32 v188, 16, v189
	v_mul_f32_e32 v1, 0xbfb8aa3b, v1
	v_mul_f32_e32 v188, 0xbfb8aa3b, v188
	v_exp_f32_e32 v1, v1
	v_mul_f32_e32 v145, 0xbfb8aa3b, v145
	v_exp_f32_e32 v194, v188
	v_and_b32_e32 v188, 0xffff0000, v189
	v_exp_f32_e32 v145, v145
	v_mul_f32_e32 v188, 0xbfb8aa3b, v188
	v_exp_f32_e32 v189, v188
	v_add_f32_e32 v1, 1.0, v1
	v_rcp_f32_e32 v188, v1
	v_add_f32_e32 v1, 1.0, v145
	v_add_f32_e32 v145, 1.0, v194
	v_rcp_f32_e32 v194, v145
	v_add_f32_e32 v145, 1.0, v189
	v_rcp_f32_e32 v195, v145
	v_rcp_f32_e32 v189, v1
	v_pk_add_f32 v[192:193], v[192:193], 1.0 op_sel_hi:[1,0]
	v_pk_add_f32 v[190:191], v[190:191], 1.0 op_sel_hi:[1,0]
	v_pk_mul_f32 v[188:189], v[192:193], v[188:189]
	v_pk_mul_f32 v[190:191], v[190:191], v[194:195]
	v_pk_mul_f32 v[88:89], v[88:89], v[188:189]
	v_pk_mul_f32 v[90:91], v[90:91], v[190:191]
.LBB0_959:
	v_lshlrev_b32_e32 v1, 16, v186
	v_max_f32_e32 v1, 0xc2700000, v1
	v_mul_f32_e32 v1, 0xbfb8aa3b, v1
	v_exp_f32_e32 v188, v1
	v_and_b32_e32 v1, 0xffff0000, v186
	v_max_f32_e32 v1, 0xc2700000, v1
	v_mul_f32_e32 v1, 0xbfb8aa3b, v1
	v_exp_f32_e32 v189, v1
	v_lshlrev_b32_e32 v1, 16, v187
	v_max_f32_e32 v1, 0xc2700000, v1
	v_mul_f32_e32 v1, 0xbfb8aa3b, v1
	v_exp_f32_e32 v186, v1
	v_and_b32_e32 v1, 0xffff0000, v187
	v_max_f32_e32 v1, 0xc2700000, v1
	v_mul_f32_e32 v1, 0xbfb8aa3b, v1
	v_exp_f32_e32 v187, v1
	s_and_b64 vcc, exec, s[4:5]
	s_mov_b64 s[38:39], -1
	s_cbranch_vccnz .LBB0_961
	v_add_f32_e32 v191, 1.0, v187
	v_add_f32_e32 v1, 1.0, v188
	v_add_f32_e32 v145, 1.0, v189
	v_add_f32_e32 v190, 1.0, v186
	v_rcp_f32_e32 v191, v191
	v_rcp_f32_e32 v1, v1
	v_rcp_f32_e32 v145, v145
	v_rcp_f32_e32 v190, v190
	v_mul_f32_e32 v191, v87, v191
	s_mov_b64 s[38:39], 0
	v_mul_f32_e32 v1, v84, v1
	v_mul_f32_e32 v145, v85, v145
	v_mul_f32_e32 v192, v86, v190
	v_cvt_pk_bf16_f32 v190, v1, v145
	v_cvt_pk_bf16_f32 v191, v192, v191
	global_store_dwordx2 v[198:199], v[190:191], off offset:288
; __device__ __forceinline__ unsigned cvt_pk_bf16(float lo, float hi) { unsigned r; asm volatile("v_cvt_pk_bf16_f32 %0, %1, %2" : "=v"(r) : "v"(lo), "v"(hi)); return r; }
;     __device__ __forceinline__ void operator()(f32x4 (&acc)[2][2][4][2], const Unit& u, int wr, int wc, int fr, int fq) const {
;     ...
;                         const unsigned long long wb = wbv[m][bj][n];
;                         f32x4 eb;
;                         eb[0] = __expf(-fmaxf(__uint_as_float((unsigned)(wb & 0xffffull) << 16), -60.f)); eb[1] = __expf(-fmaxf(__uint_as_float((unsigned)((wb >> 16) & 0xffffull) << 16), -60.f));
;                         eb[2] = __expf(-fmaxf(__uint_as_float((unsigned)((wb >> 32) & 0xffffull) << 16), -60.f)); eb[3] = __expf(-fmaxf(__uint_as_float((unsigned)((wb >> 48) & 0xffffull) << 16), -60.f));
;                         if (u.kh == 0) {
;                             const unsigned long long wa = wav[m][bj][n];
;                             f32x4 ea;
;                             ea[0] = __expf(-__uint_as_float((unsigned)(wa & 0xffffull) << 16)); ea[1] = __expf(-__uint_as_float((unsigned)((wa >> 16) & 0xffffull) << 16));
;                             ea[2] = __expf(-__uint_as_float((unsigned)((wa >> 32) & 0xffffull) << 16)); ea[3] = __expf(-__uint_as_float((unsigned)((wa >> 48) & 0xffffull) << 16));
; #pragma unroll
;                             for (int e_ = 0; e_ < 4; ++e_) acc[ai][bj][m][n][e_] *= (1.0f + eb[e_]) * __builtin_amdgcn_rcpf(1.0f + ea[e_]);
;                         } else {
;                             f32x4 o;
; #pragma unroll
;                             for (int e_ = 0; e_ < 4; ++e_) o[e_] = acc[ai][bj][m][n][e_] * __builtin_amdgcn_rcpf(1.0f + eb[e_]);
;                             *(unsigned long long*)(merged + off + bj * HALF + 16 * n) = (unsigned long long)cvt_pk_bf16(o[0], o[1]) | ((unsigned long long)cvt_pk_bf16(o[2], o[3]) << 32);
;                         } } }
.LBB0_961:
	s_andn2_b64 vcc, exec, s[38:39]
	s_cbranch_vccnz .LBB0_963
	v_lshlrev_b32_e32 v1, 16, v184
	v_and_b32_e32 v145, 0xffff0000, v184
	v_lshlrev_b32_e32 v184, 16, v185
	v_mul_f32_e32 v1, 0xbfb8aa3b, v1
	v_mul_f32_e32 v184, 0xbfb8aa3b, v184
	v_exp_f32_e32 v1, v1
	v_mul_f32_e32 v145, 0xbfb8aa3b, v145
	v_exp_f32_e32 v190, v184
	v_and_b32_e32 v184, 0xffff0000, v185
	v_exp_f32_e32 v145, v145
	v_mul_f32_e32 v184, 0xbfb8aa3b, v184
	v_exp_f32_e32 v185, v184
	v_add_f32_e32 v1, 1.0, v1
	v_rcp_f32_e32 v184, v1
	v_add_f32_e32 v1, 1.0, v145
	v_add_f32_e32 v145, 1.0, v190
	v_rcp_f32_e32 v190, v145
	v_add_f32_e32 v145, 1.0, v185
	v_rcp_f32_e32 v191, v145
	v_rcp_f32_e32 v185, v1
	v_pk_add_f32 v[188:189], v[188:189], 1.0 op_sel_hi:[1,0]
	v_pk_add_f32 v[186:187], v[186:187], 1.0 op_sel_hi:[1,0]
	v_pk_mul_f32 v[184:185], v[188:189], v[184:185]
	v_pk_mul_f32 v[186:187], v[186:187], v[190:191]
	v_pk_mul_f32 v[84:85], v[84:85], v[184:185]
	v_pk_mul_f32 v[86:87], v[86:87], v[186:187]
.LBB0_963:
	v_lshlrev_b32_e32 v1, 16, v180
	v_max_f32_e32 v1, 0xc2700000, v1
	v_mul_f32_e32 v1, 0xbfb8aa3b, v1
	v_lshlrev_b64 v[186:187], 11, v[182:183]
	v_exp_f32_e32 v182, v1
	v_and_b32_e32 v1, 0xffff0000, v180
	v_max_f32_e32 v1, 0xc2700000, v1
	v_mul_f32_e32 v1, 0xbfb8aa3b, v1
	v_exp_f32_e32 v183, v1
	v_lshlrev_b32_e32 v1, 16, v181
	v_max_f32_e32 v1, 0xc2700000, v1
	v_mul_f32_e32 v1, 0xbfb8aa3b, v1
	v_exp_f32_e32 v184, v1
	v_and_b32_e32 v1, 0xffff0000, v181
	v_max_f32_e32 v1, 0xc2700000, v1
	v_mul_f32_e32 v1, 0xbfb8aa3b, v1
	v_exp_f32_e32 v185, v1
	v_lshl_add_u64 v[180:181], s[14:15], 0, v[186:187]
	s_mov_b64 s[38:39], -1
	s_and_b64 vcc, exec, s[4:5]
	v_lshl_add_u64 v[180:181], v[2:3], 1, v[180:181]
	s_cbranch_vccnz .LBB0_965
	v_add_f32_e32 v187, 1.0, v185
	v_add_f32_e32 v1, 1.0, v182
	v_add_f32_e32 v145, 1.0, v183
	v_add_f32_e32 v186, 1.0, v184
	v_rcp_f32_e32 v187, v187
	v_rcp_f32_e32 v1, v1
	v_rcp_f32_e32 v145, v145
	v_rcp_f32_e32 v186, v186
	v_mul_f32_e32 v187, v115, v187
	s_mov_b64 s[38:39], 0
	v_mul_f32_e32 v1, v112, v1
	v_mul_f32_e32 v145, v113, v145
	v_mul_f32_e32 v188, v114, v186
	v_cvt_pk_bf16_f32 v186, v1, v145
	v_cvt_pk_bf16_f32 v187, v188, v187
	global_store_dwordx2 v[180:181], v[186:187], off
.LBB0_965:
	s_andn2_b64 vcc, exec, s[38:39]
	s_cbranch_vccnz .LBB0_967
	v_lshlrev_b32_e32 v1, 16, v178
	v_and_b32_e32 v145, 0xffff0000, v178
	v_lshlrev_b32_e32 v178, 16, v179
	v_mul_f32_e32 v1, 0xbfb8aa3b, v1
	v_mul_f32_e32 v178, 0xbfb8aa3b, v178
	v_exp_f32_e32 v1, v1
	v_mul_f32_e32 v145, 0xbfb8aa3b, v145
	v_exp_f32_e32 v186, v178
	v_and_b32_e32 v178, 0xffff0000, v179
	v_exp_f32_e32 v145, v145
	v_mul_f32_e32 v178, 0xbfb8aa3b, v178
	v_exp_f32_e32 v179, v178
	v_add_f32_e32 v1, 1.0, v1
	v_rcp_f32_e32 v178, v1
	v_add_f32_e32 v1, 1.0, v145
	v_add_f32_e32 v145, 1.0, v186
	v_rcp_f32_e32 v186, v145
	v_add_f32_e32 v145, 1.0, v179
	v_rcp_f32_e32 v187, v145
	v_rcp_f32_e32 v179, v1
	v_pk_add_f32 v[182:183], v[182:183], 1.0 op_sel_hi:[1,0]
	v_pk_add_f32 v[184:185], v[184:185], 1.0 op_sel_hi:[1,0]
	v_pk_mul_f32 v[178:179], v[182:183], v[178:179]
	v_pk_mul_f32 v[184:185], v[184:185], v[186:187]
	v_pk_mul_f32 v[112:113], v[112:113], v[178:179]
	v_pk_mul_f32 v[114:115], v[114:115], v[184:185]
.LBB0_967:
	v_lshlrev_b32_e32 v1, 16, v176
	v_max_f32_e32 v1, 0xc2700000, v1
	v_mul_f32_e32 v1, 0xbfb8aa3b, v1
	v_exp_f32_e32 v178, v1
	v_and_b32_e32 v1, 0xffff0000, v176
	v_max_f32_e32 v1, 0xc2700000, v1
	v_mul_f32_e32 v1, 0xbfb8aa3b, v1
	v_exp_f32_e32 v179, v1
	v_lshlrev_b32_e32 v1, 16, v177
	v_max_f32_e32 v1, 0xc2700000, v1
	v_mul_f32_e32 v1, 0xbfb8aa3b, v1
	v_exp_f32_e32 v176, v1
	v_and_b32_e32 v1, 0xffff0000, v177
	v_max_f32_e32 v1, 0xc2700000, v1
	v_mul_f32_e32 v1, 0xbfb8aa3b, v1
	v_exp_f32_e32 v177, v1
	s_and_b64 vcc, exec, s[4:5]
	s_mov_b64 s[38:39], -1
	s_cbranch_vccnz .LBB0_969
	v_add_f32_e32 v183, 1.0, v177
	v_add_f32_e32 v1, 1.0, v178
	v_add_f32_e32 v145, 1.0, v179
	v_add_f32_e32 v182, 1.0, v176
	v_rcp_f32_e32 v183, v183
	v_rcp_f32_e32 v1, v1
	v_rcp_f32_e32 v145, v145
	v_rcp_f32_e32 v182, v182
	v_mul_f32_e32 v183, v111, v183
	s_mov_b64 s[38:39], 0
	v_mul_f32_e32 v1, v108, v1
	v_mul_f32_e32 v145, v109, v145
	v_mul_f32_e32 v184, v110, v182
	v_cvt_pk_bf16_f32 v182, v1, v145
	v_cvt_pk_bf16_f32 v183, v184, v183
	global_store_dwordx2 v[180:181], v[182:183], off offset:32
.LBB0_969:
	s_andn2_b64 vcc, exec, s[38:39]
	s_cbranch_vccnz .LBB0_971
	v_lshlrev_b32_e32 v1, 16, v174
	v_and_b32_e32 v145, 0xffff0000, v174
	v_lshlrev_b32_e32 v174, 16, v175
	v_mul_f32_e32 v1, 0xbfb8aa3b, v1
	v_mul_f32_e32 v174, 0xbfb8aa3b, v174
	v_exp_f32_e32 v1, v1
	v_mul_f32_e32 v145, 0xbfb8aa3b, v145
	v_exp_f32_e32 v182, v174
	v_and_b32_e32 v174, 0xffff0000, v175
	v_exp_f32_e32 v145, v145
	v_mul_f32_e32 v174, 0xbfb8aa3b, v174
	v_exp_f32_e32 v175, v174
	v_add_f32_e32 v1, 1.0, v1
	v_rcp_f32_e32 v174, v1
	v_add_f32_e32 v1, 1.0, v145
	v_add_f32_e32 v145, 1.0, v182
	v_rcp_f32_e32 v182, v145
	v_add_f32_e32 v145, 1.0, v175
	v_rcp_f32_e32 v183, v145
	v_rcp_f32_e32 v175, v1
	v_pk_add_f32 v[178:179], v[178:179], 1.0 op_sel_hi:[1,0]
	v_pk_add_f32 v[176:177], v[176:177], 1.0 op_sel_hi:[1,0]
	v_pk_mul_f32 v[174:175], v[178:179], v[174:175]
	v_pk_mul_f32 v[176:177], v[176:177], v[182:183]
	v_pk_mul_f32 v[108:109], v[108:109], v[174:175]
	v_pk_mul_f32 v[110:111], v[110:111], v[176:177]
; __device__ __forceinline__ unsigned cvt_pk_bf16(float lo, float hi) { unsigned r; asm volatile("v_cvt_pk_bf16_f32 %0, %1, %2" : "=v"(r) : "v"(lo), "v"(hi)); return r; }
;     __device__ __forceinline__ void operator()(f32x4 (&acc)[2][2][4][2], const Unit& u, int wr, int wc, int fr, int fq) const {
;     ...
;                         const unsigned long long wb = wbv[m][bj][n];
;                         f32x4 eb;
;                         eb[0] = __expf(-fmaxf(__uint_as_float((unsigned)(wb & 0xffffull) << 16), -60.f)); eb[1] = __expf(-fmaxf(__uint_as_float((unsigned)((wb >> 16) & 0xffffull) << 16), -60.f));
;                         eb[2] = __expf(-fmaxf(__uint_as_float((unsigned)((wb >> 32) & 0xffffull) << 16), -60.f)); eb[3] = __expf(-fmaxf(__uint_as_float((unsigned)((wb >> 48) & 0xffffull) << 16), -60.f));
;                         if (u.kh == 0) {
;                             const unsigned long long wa = wav[m][bj][n];
;                             f32x4 ea;
;                             ea[0] = __expf(-__uint_as_float((unsigned)(wa & 0xffffull) << 16)); ea[1] = __expf(-__uint_as_float((unsigned)((wa >> 16) & 0xffffull) << 16));
;                             ea[2] = __expf(-__uint_as_float((unsigned)((wa >> 32) & 0xffffull) << 16)); ea[3] = __expf(-__uint_as_float((unsigned)((wa >> 48) & 0xffffull) << 16));
; #pragma unroll
;                             for (int e_ = 0; e_ < 4; ++e_) acc[ai][bj][m][n][e_] *= (1.0f + eb[e_]) * __builtin_amdgcn_rcpf(1.0f + ea[e_]);
;                         } else {
;                             f32x4 o;
; #pragma unroll
;                             for (int e_ = 0; e_ < 4; ++e_) o[e_] = acc[ai][bj][m][n][e_] * __builtin_amdgcn_rcpf(1.0f + eb[e_]);
;                             *(unsigned long long*)(merged + off + bj * HALF + 16 * n) = (unsigned long long)cvt_pk_bf16(o[0], o[1]) | ((unsigned long long)cvt_pk_bf16(o[2], o[3]) << 32);
;                         } } }
.LBB0_971:
	v_lshlrev_b32_e32 v1, 16, v172
	v_max_f32_e32 v1, 0xc2700000, v1
	v_mul_f32_e32 v1, 0xbfb8aa3b, v1
	v_exp_f32_e32 v174, v1
	v_and_b32_e32 v1, 0xffff0000, v172
	v_max_f32_e32 v1, 0xc2700000, v1
	v_mul_f32_e32 v1, 0xbfb8aa3b, v1
	v_exp_f32_e32 v175, v1
	v_lshlrev_b32_e32 v1, 16, v173
	v_max_f32_e32 v1, 0xc2700000, v1
	v_mul_f32_e32 v1, 0xbfb8aa3b, v1
	v_exp_f32_e32 v172, v1
	v_and_b32_e32 v1, 0xffff0000, v173
	v_max_f32_e32 v1, 0xc2700000, v1
	v_mul_f32_e32 v1, 0xbfb8aa3b, v1
	v_exp_f32_e32 v173, v1
	s_and_b64 vcc, exec, s[4:5]
	s_mov_b64 s[38:39], -1
	s_cbranch_vccnz .LBB0_973
	v_add_f32_e32 v177, 1.0, v173
	v_add_f32_e32 v1, 1.0, v174
	v_add_f32_e32 v145, 1.0, v175
	v_add_f32_e32 v176, 1.0, v172
	v_rcp_f32_e32 v177, v177
	v_rcp_f32_e32 v1, v1
	v_rcp_f32_e32 v145, v145
	v_rcp_f32_e32 v176, v176
	v_mul_f32_e32 v177, v83, v177
	s_mov_b64 s[38:39], 0
	v_mul_f32_e32 v1, v80, v1
	v_mul_f32_e32 v145, v81, v145
	v_mul_f32_e32 v178, v82, v176
	v_cvt_pk_bf16_f32 v176, v1, v145
	v_cvt_pk_bf16_f32 v177, v178, v177
	global_store_dwordx2 v[180:181], v[176:177], off offset:256
.LBB0_973:
	s_andn2_b64 vcc, exec, s[38:39]
	s_cbranch_vccnz .LBB0_975
	v_lshlrev_b32_e32 v1, 16, v170
	v_and_b32_e32 v145, 0xffff0000, v170
	v_lshlrev_b32_e32 v170, 16, v171
	v_mul_f32_e32 v1, 0xbfb8aa3b, v1
	v_mul_f32_e32 v170, 0xbfb8aa3b, v170
	v_exp_f32_e32 v1, v1
	v_mul_f32_e32 v145, 0xbfb8aa3b, v145
	v_exp_f32_e32 v176, v170
	v_and_b32_e32 v170, 0xffff0000, v171
	v_exp_f32_e32 v145, v145
	v_mul_f32_e32 v170, 0xbfb8aa3b, v170
	v_exp_f32_e32 v171, v170
	v_add_f32_e32 v1, 1.0, v1
	v_rcp_f32_e32 v170, v1
	v_add_f32_e32 v1, 1.0, v145
	v_add_f32_e32 v145, 1.0, v176
	v_rcp_f32_e32 v176, v145
	v_add_f32_e32 v145, 1.0, v171
	v_rcp_f32_e32 v177, v145
	v_rcp_f32_e32 v171, v1
	v_pk_add_f32 v[174:175], v[174:175], 1.0 op_sel_hi:[1,0]
	v_pk_add_f32 v[172:173], v[172:173], 1.0 op_sel_hi:[1,0]
	v_pk_mul_f32 v[170:171], v[174:175], v[170:171]
	v_pk_mul_f32 v[172:173], v[172:173], v[176:177]
	v_pk_mul_f32 v[80:81], v[80:81], v[170:171]
	v_pk_mul_f32 v[82:83], v[82:83], v[172:173]
.LBB0_975:
	v_lshlrev_b32_e32 v1, 16, v168
	v_max_f32_e32 v1, 0xc2700000, v1
	v_mul_f32_e32 v1, 0xbfb8aa3b, v1
	v_exp_f32_e32 v170, v1
	v_and_b32_e32 v1, 0xffff0000, v168
	v_max_f32_e32 v1, 0xc2700000, v1
	v_mul_f32_e32 v1, 0xbfb8aa3b, v1
	v_exp_f32_e32 v171, v1
	v_lshlrev_b32_e32 v1, 16, v169
	v_max_f32_e32 v1, 0xc2700000, v1
	v_mul_f32_e32 v1, 0xbfb8aa3b, v1
	v_exp_f32_e32 v168, v1
	v_and_b32_e32 v1, 0xffff0000, v169
	v_max_f32_e32 v1, 0xc2700000, v1
	v_mul_f32_e32 v1, 0xbfb8aa3b, v1
	v_exp_f32_e32 v169, v1
	s_and_b64 vcc, exec, s[4:5]
	s_mov_b64 s[38:39], -1
	s_cbranch_vccnz .LBB0_977
	v_add_f32_e32 v173, 1.0, v169
	v_add_f32_e32 v1, 1.0, v170
	v_add_f32_e32 v145, 1.0, v171
	v_add_f32_e32 v172, 1.0, v168
	v_rcp_f32_e32 v173, v173
	v_rcp_f32_e32 v1, v1
	v_rcp_f32_e32 v145, v145
	v_rcp_f32_e32 v172, v172
	v_mul_f32_e32 v173, v79, v173
	s_mov_b64 s[38:39], 0
	v_mul_f32_e32 v1, v76, v1
	v_mul_f32_e32 v145, v77, v145
	v_mul_f32_e32 v174, v78, v172
	v_cvt_pk_bf16_f32 v172, v1, v145
	v_cvt_pk_bf16_f32 v173, v174, v173
	global_store_dwordx2 v[180:181], v[172:173], off offset:288
.LBB0_977:
	s_andn2_b64 vcc, exec, s[38:39]
	s_cbranch_vccnz .LBB0_979
	v_lshlrev_b32_e32 v1, 16, v166
	v_and_b32_e32 v145, 0xffff0000, v166
	v_lshlrev_b32_e32 v166, 16, v167
	v_mul_f32_e32 v1, 0xbfb8aa3b, v1
	v_mul_f32_e32 v166, 0xbfb8aa3b, v166
	v_exp_f32_e32 v1, v1
	v_mul_f32_e32 v145, 0xbfb8aa3b, v145
	v_exp_f32_e32 v172, v166
	v_and_b32_e32 v166, 0xffff0000, v167
	v_exp_f32_e32 v145, v145
	v_mul_f32_e32 v166, 0xbfb8aa3b, v166
	v_exp_f32_e32 v167, v166
	v_add_f32_e32 v1, 1.0, v1
	v_rcp_f32_e32 v166, v1
	v_add_f32_e32 v1, 1.0, v145
	v_add_f32_e32 v145, 1.0, v172
	v_rcp_f32_e32 v172, v145
	v_add_f32_e32 v145, 1.0, v167
	v_rcp_f32_e32 v173, v145
	v_rcp_f32_e32 v167, v1
	v_pk_add_f32 v[170:171], v[170:171], 1.0 op_sel_hi:[1,0]
	v_pk_add_f32 v[168:169], v[168:169], 1.0 op_sel_hi:[1,0]
	v_pk_mul_f32 v[166:167], v[170:171], v[166:167]
	v_pk_mul_f32 v[168:169], v[168:169], v[172:173]
	v_pk_mul_f32 v[76:77], v[76:77], v[166:167]
	v_pk_mul_f32 v[78:79], v[78:79], v[168:169]
.LBB0_979:
	v_lshlrev_b32_e32 v1, 16, v162
	v_max_f32_e32 v1, 0xc2700000, v1
	v_mul_f32_e32 v1, 0xbfb8aa3b, v1
	v_lshlrev_b64 v[168:169], 11, v[164:165]
	v_exp_f32_e32 v164, v1
	v_and_b32_e32 v1, 0xffff0000, v162
	v_max_f32_e32 v1, 0xc2700000, v1
	v_mul_f32_e32 v1, 0xbfb8aa3b, v1
	v_exp_f32_e32 v165, v1
	v_lshlrev_b32_e32 v1, 16, v163
	v_max_f32_e32 v1, 0xc2700000, v1
	v_mul_f32_e32 v1, 0xbfb8aa3b, v1
	v_exp_f32_e32 v166, v1
	v_and_b32_e32 v1, 0xffff0000, v163
	v_max_f32_e32 v1, 0xc2700000, v1
	v_mul_f32_e32 v1, 0xbfb8aa3b, v1
	v_exp_f32_e32 v167, v1
	v_lshl_add_u64 v[162:163], s[14:15], 0, v[168:169]
	s_mov_b64 s[38:39], -1
	s_and_b64 vcc, exec, s[4:5]
	v_lshl_add_u64 v[162:163], v[2:3], 1, v[162:163]
	s_cbranch_vccnz .LBB0_981
	v_add_f32_e32 v169, 1.0, v167
	v_add_f32_e32 v1, 1.0, v164
	v_add_f32_e32 v145, 1.0, v165
	v_add_f32_e32 v168, 1.0, v166
	v_rcp_f32_e32 v169, v169
	v_rcp_f32_e32 v1, v1
	v_rcp_f32_e32 v145, v145
	v_rcp_f32_e32 v168, v168
	v_mul_f32_e32 v169, v107, v169
	s_mov_b64 s[38:39], 0
	v_mul_f32_e32 v1, v104, v1
	v_mul_f32_e32 v145, v105, v145
	v_mul_f32_e32 v170, v106, v168
	v_cvt_pk_bf16_f32 v168, v1, v145
	v_cvt_pk_bf16_f32 v169, v170, v169
	global_store_dwordx2 v[162:163], v[168:169], off
; __device__ __forceinline__ unsigned cvt_pk_bf16(float lo, float hi) { unsigned r; asm volatile("v_cvt_pk_bf16_f32 %0, %1, %2" : "=v"(r) : "v"(lo), "v"(hi)); return r; }
;     __device__ __forceinline__ void operator()(f32x4 (&acc)[2][2][4][2], const Unit& u, int wr, int wc, int fr, int fq) const {
;     ...
;                         const unsigned long long wb = wbv[m][bj][n];
;                         f32x4 eb;
;                         eb[0] = __expf(-fmaxf(__uint_as_float((unsigned)(wb & 0xffffull) << 16), -60.f)); eb[1] = __expf(-fmaxf(__uint_as_float((unsigned)((wb >> 16) & 0xffffull) << 16), -60.f));
;                         eb[2] = __expf(-fmaxf(__uint_as_float((unsigned)((wb >> 32) & 0xffffull) << 16), -60.f)); eb[3] = __expf(-fmaxf(__uint_as_float((unsigned)((wb >> 48) & 0xffffull) << 16), -60.f));
;                         if (u.kh == 0) {
;                             const unsigned long long wa = wav[m][bj][n];
;                             f32x4 ea;
;                             ea[0] = __expf(-__uint_as_float((unsigned)(wa & 0xffffull) << 16)); ea[1] = __expf(-__uint_as_float((unsigned)((wa >> 16) & 0xffffull) << 16));
;                             ea[2] = __expf(-__uint_as_float((unsigned)((wa >> 32) & 0xffffull) << 16)); ea[3] = __expf(-__uint_as_float((unsigned)((wa >> 48) & 0xffffull) << 16));
; #pragma unroll
;                             for (int e_ = 0; e_ < 4; ++e_) acc[ai][bj][m][n][e_] *= (1.0f + eb[e_]) * __builtin_amdgcn_rcpf(1.0f + ea[e_]);
;                         } else {
;                             f32x4 o;
; #pragma unroll
;                             for (int e_ = 0; e_ < 4; ++e_) o[e_] = acc[ai][bj][m][n][e_] * __builtin_amdgcn_rcpf(1.0f + eb[e_]);
;                             *(unsigned long long*)(merged + off + bj * HALF + 16 * n) = (unsigned long long)cvt_pk_bf16(o[0], o[1]) | ((unsigned long long)cvt_pk_bf16(o[2], o[3]) << 32);
.LBB0_981:
	s_andn2_b64 vcc, exec, s[38:39]
	s_cbranch_vccnz .LBB0_983
	v_lshlrev_b32_e32 v1, 16, v160
	v_and_b32_e32 v145, 0xffff0000, v160
	v_lshlrev_b32_e32 v160, 16, v161
	v_mul_f32_e32 v1, 0xbfb8aa3b, v1
	v_mul_f32_e32 v160, 0xbfb8aa3b, v160
	v_exp_f32_e32 v1, v1
	v_mul_f32_e32 v145, 0xbfb8aa3b, v145
	v_exp_f32_e32 v168, v160
	v_and_b32_e32 v160, 0xffff0000, v161
	v_exp_f32_e32 v145, v145
	v_mul_f32_e32 v160, 0xbfb8aa3b, v160
	v_exp_f32_e32 v161, v160
	v_add_f32_e32 v1, 1.0, v1
	v_rcp_f32_e32 v160, v1
	v_add_f32_e32 v1, 1.0, v145
	v_add_f32_e32 v145, 1.0, v168
	v_rcp_f32_e32 v168, v145
	v_add_f32_e32 v145, 1.0, v161
	v_rcp_f32_e32 v169, v145
	v_rcp_f32_e32 v161, v1
	v_pk_add_f32 v[164:165], v[164:165], 1.0 op_sel_hi:[1,0]
	v_pk_add_f32 v[166:167], v[166:167], 1.0 op_sel_hi:[1,0]
	v_pk_mul_f32 v[160:161], v[164:165], v[160:161]
	v_pk_mul_f32 v[166:167], v[166:167], v[168:169]
	v_pk_mul_f32 v[104:105], v[104:105], v[160:161]
	v_pk_mul_f32 v[106:107], v[106:107], v[166:167]
.LBB0_983:
	v_lshlrev_b32_e32 v1, 16, v158
	v_max_f32_e32 v1, 0xc2700000, v1
	v_mul_f32_e32 v1, 0xbfb8aa3b, v1
	v_exp_f32_e32 v160, v1
	v_and_b32_e32 v1, 0xffff0000, v158
	v_max_f32_e32 v1, 0xc2700000, v1
	v_mul_f32_e32 v1, 0xbfb8aa3b, v1
	v_exp_f32_e32 v161, v1
	v_lshlrev_b32_e32 v1, 16, v159
	v_max_f32_e32 v1, 0xc2700000, v1
	v_mul_f32_e32 v1, 0xbfb8aa3b, v1
	v_exp_f32_e32 v158, v1
	v_and_b32_e32 v1, 0xffff0000, v159
	v_max_f32_e32 v1, 0xc2700000, v1
	v_mul_f32_e32 v1, 0xbfb8aa3b, v1
	v_exp_f32_e32 v159, v1
	s_and_b64 vcc, exec, s[4:5]
	s_mov_b64 s[38:39], -1
	s_cbranch_vccnz .LBB0_985
	v_add_f32_e32 v165, 1.0, v159
	v_add_f32_e32 v1, 1.0, v160
	v_add_f32_e32 v145, 1.0, v161
	v_add_f32_e32 v164, 1.0, v158
	v_rcp_f32_e32 v165, v165
	v_rcp_f32_e32 v1, v1
	v_rcp_f32_e32 v145, v145
	v_rcp_f32_e32 v164, v164
	v_mul_f32_e32 v165, v103, v165
	s_mov_b64 s[38:39], 0
	v_mul_f32_e32 v1, v100, v1
	v_mul_f32_e32 v145, v101, v145
	v_mul_f32_e32 v166, v102, v164
	v_cvt_pk_bf16_f32 v164, v1, v145
	v_cvt_pk_bf16_f32 v165, v166, v165
	global_store_dwordx2 v[162:163], v[164:165], off offset:32
.LBB0_985:
	s_andn2_b64 vcc, exec, s[38:39]
	s_cbranch_vccnz .LBB0_987
	v_lshlrev_b32_e32 v1, 16, v156
	v_and_b32_e32 v145, 0xffff0000, v156
	v_lshlrev_b32_e32 v156, 16, v157
	v_mul_f32_e32 v1, 0xbfb8aa3b, v1
	v_mul_f32_e32 v156, 0xbfb8aa3b, v156
	v_exp_f32_e32 v1, v1
	v_mul_f32_e32 v145, 0xbfb8aa3b, v145
	v_exp_f32_e32 v164, v156
	v_and_b32_e32 v156, 0xffff0000, v157
	v_exp_f32_e32 v145, v145
	v_mul_f32_e32 v156, 0xbfb8aa3b, v156
	v_exp_f32_e32 v157, v156
	v_add_f32_e32 v1, 1.0, v1
	v_rcp_f32_e32 v156, v1
	v_add_f32_e32 v1, 1.0, v145
	v_add_f32_e32 v145, 1.0, v164
	v_rcp_f32_e32 v164, v145
	v_add_f32_e32 v145, 1.0, v157
	v_rcp_f32_e32 v165, v145
	v_rcp_f32_e32 v157, v1
	v_pk_add_f32 v[160:161], v[160:161], 1.0 op_sel_hi:[1,0]
	v_pk_add_f32 v[158:159], v[158:159], 1.0 op_sel_hi:[1,0]
	v_pk_mul_f32 v[156:157], v[160:161], v[156:157]
	v_pk_mul_f32 v[158:159], v[158:159], v[164:165]
	v_pk_mul_f32 v[100:101], v[100:101], v[156:157]
	v_pk_mul_f32 v[102:103], v[102:103], v[158:159]
; __device__ __forceinline__ unsigned cvt_pk_bf16(float lo, float hi) { unsigned r; asm volatile("v_cvt_pk_bf16_f32 %0, %1, %2" : "=v"(r) : "v"(lo), "v"(hi)); return r; }
;     __device__ __forceinline__ void operator()(f32x4 (&acc)[2][2][4][2], const Unit& u, int wr, int wc, int fr, int fq) const {
;     ...
;                         const unsigned long long wb = wbv[m][bj][n];
;                         f32x4 eb;
;                         eb[0] = __expf(-fmaxf(__uint_as_float((unsigned)(wb & 0xffffull) << 16), -60.f)); eb[1] = __expf(-fmaxf(__uint_as_float((unsigned)((wb >> 16) & 0xffffull) << 16), -60.f));
;                         eb[2] = __expf(-fmaxf(__uint_as_float((unsigned)((wb >> 32) & 0xffffull) << 16), -60.f)); eb[3] = __expf(-fmaxf(__uint_as_float((unsigned)((wb >> 48) & 0xffffull) << 16), -60.f));
;                         if (u.kh == 0) {
;                             const unsigned long long wa = wav[m][bj][n];
;                             f32x4 ea;
;                             ea[0] = __expf(-__uint_as_float((unsigned)(wa & 0xffffull) << 16)); ea[1] = __expf(-__uint_as_float((unsigned)((wa >> 16) & 0xffffull) << 16));
;                             ea[2] = __expf(-__uint_as_float((unsigned)((wa >> 32) & 0xffffull) << 16)); ea[3] = __expf(-__uint_as_float((unsigned)((wa >> 48) & 0xffffull) << 16));
; #pragma unroll
;                             for (int e_ = 0; e_ < 4; ++e_) acc[ai][bj][m][n][e_] *= (1.0f + eb[e_]) * __builtin_amdgcn_rcpf(1.0f + ea[e_]);
;                         } else {
;                             f32x4 o;
; #pragma unroll
;                             for (int e_ = 0; e_ < 4; ++e_) o[e_] = acc[ai][bj][m][n][e_] * __builtin_amdgcn_rcpf(1.0f + eb[e_]);
;                             *(unsigned long long*)(merged + off + bj * HALF + 16 * n) = (unsigned long long)cvt_pk_bf16(o[0], o[1]) | ((unsigned long long)cvt_pk_bf16(o[2], o[3]) << 32);
.LBB0_987:
	v_lshlrev_b32_e32 v1, 16, v154
	v_max_f32_e32 v1, 0xc2700000, v1
	v_mul_f32_e32 v1, 0xbfb8aa3b, v1
	v_exp_f32_e32 v156, v1
	v_and_b32_e32 v1, 0xffff0000, v154
	v_max_f32_e32 v1, 0xc2700000, v1
	v_mul_f32_e32 v1, 0xbfb8aa3b, v1
	v_exp_f32_e32 v157, v1
	v_lshlrev_b32_e32 v1, 16, v155
	v_max_f32_e32 v1, 0xc2700000, v1
	v_mul_f32_e32 v1, 0xbfb8aa3b, v1
	v_exp_f32_e32 v154, v1
	v_and_b32_e32 v1, 0xffff0000, v155
	v_max_f32_e32 v1, 0xc2700000, v1
	v_mul_f32_e32 v1, 0xbfb8aa3b, v1
	v_exp_f32_e32 v155, v1
	s_and_b64 vcc, exec, s[4:5]
	s_mov_b64 s[38:39], -1
	s_cbranch_vccnz .LBB0_989
	v_add_f32_e32 v159, 1.0, v155
	v_add_f32_e32 v1, 1.0, v156
	v_add_f32_e32 v145, 1.0, v157
	v_add_f32_e32 v158, 1.0, v154
	v_rcp_f32_e32 v159, v159
	v_rcp_f32_e32 v1, v1
	v_rcp_f32_e32 v145, v145
	v_rcp_f32_e32 v158, v158
	v_mul_f32_e32 v159, v75, v159
	s_mov_b64 s[38:39], 0
	v_mul_f32_e32 v1, v72, v1
	v_mul_f32_e32 v145, v73, v145
	v_mul_f32_e32 v160, v74, v158
	v_cvt_pk_bf16_f32 v158, v1, v145
	v_cvt_pk_bf16_f32 v159, v160, v159
	global_store_dwordx2 v[162:163], v[158:159], off offset:256
.LBB0_989:
	s_andn2_b64 vcc, exec, s[38:39]
	s_cbranch_vccnz .LBB0_991
	v_lshlrev_b32_e32 v1, 16, v152
	v_and_b32_e32 v145, 0xffff0000, v152
	v_lshlrev_b32_e32 v152, 16, v153
	v_mul_f32_e32 v1, 0xbfb8aa3b, v1
	v_mul_f32_e32 v152, 0xbfb8aa3b, v152
	v_exp_f32_e32 v1, v1
	v_mul_f32_e32 v145, 0xbfb8aa3b, v145
	v_exp_f32_e32 v158, v152
	v_and_b32_e32 v152, 0xffff0000, v153
	v_exp_f32_e32 v145, v145
	v_mul_f32_e32 v152, 0xbfb8aa3b, v152
	v_exp_f32_e32 v153, v152
	v_add_f32_e32 v1, 1.0, v1
	v_rcp_f32_e32 v152, v1
	v_add_f32_e32 v1, 1.0, v145
	v_add_f32_e32 v145, 1.0, v158
	v_rcp_f32_e32 v158, v145
	v_add_f32_e32 v145, 1.0, v153
	v_rcp_f32_e32 v159, v145
	v_rcp_f32_e32 v153, v1
	v_pk_add_f32 v[156:157], v[156:157], 1.0 op_sel_hi:[1,0]
	v_pk_add_f32 v[154:155], v[154:155], 1.0 op_sel_hi:[1,0]
	v_pk_mul_f32 v[152:153], v[156:157], v[152:153]
	v_pk_mul_f32 v[154:155], v[154:155], v[158:159]
	v_pk_mul_f32 v[72:73], v[72:73], v[152:153]
	v_pk_mul_f32 v[74:75], v[74:75], v[154:155]
.LBB0_991:
	v_lshlrev_b32_e32 v1, 16, v150
	v_max_f32_e32 v1, 0xc2700000, v1
	v_mul_f32_e32 v1, 0xbfb8aa3b, v1
	v_exp_f32_e32 v152, v1
	v_and_b32_e32 v1, 0xffff0000, v150
	v_max_f32_e32 v1, 0xc2700000, v1
	v_mul_f32_e32 v1, 0xbfb8aa3b, v1
	v_exp_f32_e32 v153, v1
	v_lshlrev_b32_e32 v1, 16, v151
	v_max_f32_e32 v1, 0xc2700000, v1
	v_mul_f32_e32 v1, 0xbfb8aa3b, v1
	v_exp_f32_e32 v150, v1
	v_and_b32_e32 v1, 0xffff0000, v151
	v_max_f32_e32 v1, 0xc2700000, v1
	v_mul_f32_e32 v1, 0xbfb8aa3b, v1
	v_exp_f32_e32 v151, v1
	s_and_b64 vcc, exec, s[4:5]
	s_mov_b64 s[38:39], -1
	s_cbranch_vccnz .LBB0_993
	v_add_f32_e32 v155, 1.0, v151
	v_add_f32_e32 v1, 1.0, v152
	v_add_f32_e32 v145, 1.0, v153
	v_add_f32_e32 v154, 1.0, v150
	v_rcp_f32_e32 v155, v155
	v_rcp_f32_e32 v1, v1
	v_rcp_f32_e32 v145, v145
	v_rcp_f32_e32 v154, v154
	v_mul_f32_e32 v155, v71, v155
	s_mov_b64 s[38:39], 0
	v_mul_f32_e32 v1, v68, v1
	v_mul_f32_e32 v145, v69, v145
	v_mul_f32_e32 v156, v70, v154
	v_cvt_pk_bf16_f32 v154, v1, v145
	v_cvt_pk_bf16_f32 v155, v156, v155
	global_store_dwordx2 v[162:163], v[154:155], off offset:288
.LBB0_993:
	s_andn2_b64 vcc, exec, s[38:39]
	s_cbranch_vccnz .LBB0_995
	v_lshlrev_b32_e32 v1, 16, v148
	v_and_b32_e32 v145, 0xffff0000, v148
	v_lshlrev_b32_e32 v148, 16, v149
	v_mul_f32_e32 v1, 0xbfb8aa3b, v1
	v_mul_f32_e32 v148, 0xbfb8aa3b, v148
	v_exp_f32_e32 v1, v1
	v_mul_f32_e32 v145, 0xbfb8aa3b, v145
	v_exp_f32_e32 v154, v148
	v_and_b32_e32 v148, 0xffff0000, v149
	v_exp_f32_e32 v145, v145
	v_mul_f32_e32 v148, 0xbfb8aa3b, v148
	v_exp_f32_e32 v149, v148
	v_add_f32_e32 v1, 1.0, v1
	v_rcp_f32_e32 v148, v1
	v_add_f32_e32 v1, 1.0, v145
	v_add_f32_e32 v145, 1.0, v154
	v_rcp_f32_e32 v154, v145
	v_add_f32_e32 v145, 1.0, v149
	v_rcp_f32_e32 v155, v145
	v_rcp_f32_e32 v149, v1
	v_pk_add_f32 v[152:153], v[152:153], 1.0 op_sel_hi:[1,0]
	v_pk_add_f32 v[150:151], v[150:151], 1.0 op_sel_hi:[1,0]
	v_pk_mul_f32 v[148:149], v[152:153], v[148:149]
	v_pk_mul_f32 v[150:151], v[150:151], v[154:155]
	v_pk_mul_f32 v[68:69], v[68:69], v[148:149]
	v_pk_mul_f32 v[70:71], v[70:71], v[150:151]

; __device__ __forceinline__ unsigned cvt_pk_bf16(float lo, float hi) { unsigned r; asm volatile("v_cvt_pk_bf16_f32 %0, %1, %2" : "=v"(r) : "v"(lo), "v"(hi)); return r; }
;     __device__ __forceinline__ void operator()(f32x4 (&acc)[2][2][4][2], const Unit& u, int wr, int wc, int fr, int fq) const {
;     ...
;                         const unsigned long long wb = wbv[m][bj][n];
;                         f32x4 eb;
;                         eb[0] = __expf(-fmaxf(__uint_as_float((unsigned)(wb & 0xffffull) << 16), -60.f)); eb[1] = __expf(-fmaxf(__uint_as_float((unsigned)((wb >> 16) & 0xffffull) << 16), -60.f));
;                         eb[2] = __expf(-fmaxf(__uint_as_float((unsigned)((wb >> 32) & 0xffffull) << 16), -60.f)); eb[3] = __expf(-fmaxf(__uint_as_float((unsigned)((wb >> 48) & 0xffffull) << 16), -60.f));
;                         if (u.kh == 0) {
;                             const unsigned long long wa = wav[m][bj][n];
;                             f32x4 ea;
;                             ea[0] = __expf(-__uint_as_float((unsigned)(wa & 0xffffull) << 16)); ea[1] = __expf(-__uint_as_float((unsigned)((wa >> 16) & 0xffffull) << 16));
;                             ea[2] = __expf(-__uint_as_float((unsigned)((wa >> 32) & 0xffffull) << 16)); ea[3] = __expf(-__uint_as_float((unsigned)((wa >> 48) & 0xffffull) << 16));
; #pragma unroll
;                             for (int e_ = 0; e_ < 4; ++e_) acc[ai][bj][m][n][e_] *= (1.0f + eb[e_]) * __builtin_amdgcn_rcpf(1.0f + ea[e_]);
;                         } else {
;                             f32x4 o;
; #pragma unroll
;                             for (int e_ = 0; e_ < 4; ++e_) o[e_] = acc[ai][bj][m][n][e_] * __builtin_amdgcn_rcpf(1.0f + eb[e_]);
;                             *(unsigned long long*)(merged + off + bj * HALF + 16 * n) = (unsigned long long)cvt_pk_bf16(o[0], o[1]) | ((unsigned long long)cvt_pk_bf16(o[2], o[3]) << 32);
.LBB0_1011:
	s_waitcnt vmcnt(15)
	v_lshlrev_b32_e32 v1, 16, v208
	v_max_f32_e32 v1, 0xc2700000, v1
	v_mul_f32_e32 v1, 0xbfb8aa3b, v1
	v_lshlrev_b64 v[218:219], 11, v[214:215]
	v_exp_f32_e32 v214, v1
	v_and_b32_e32 v1, 0xffff0000, v208
	v_max_f32_e32 v1, 0xc2700000, v1
	v_mul_f32_e32 v1, 0xbfb8aa3b, v1
	v_exp_f32_e32 v215, v1
	v_lshlrev_b32_e32 v1, 16, v209
	v_max_f32_e32 v1, 0xc2700000, v1
	v_mul_f32_e32 v1, 0xbfb8aa3b, v1
	v_exp_f32_e32 v216, v1
	v_and_b32_e32 v1, 0xffff0000, v209
	v_max_f32_e32 v1, 0xc2700000, v1
	v_mul_f32_e32 v1, 0xbfb8aa3b, v1
	v_exp_f32_e32 v217, v1
	v_lshl_add_u64 v[208:209], s[14:15], 0, v[218:219]
	s_mov_b64 s[6:7], -1
	s_and_b64 vcc, exec, s[4:5]
	v_lshl_add_u64 v[208:209], v[2:3], 1, v[208:209]
	s_cbranch_vccnz .LBB0_1013
	v_add_f32_e32 v218, 1.0, v215
	v_add_f32_e32 v219, 1.0, v216
	v_add_f32_e32 v1, 1.0, v214
	v_rcp_f32_e32 v218, v218
	v_rcp_f32_e32 v219, v219
	v_add_f32_e32 v220, 1.0, v217
	v_rcp_f32_e32 v1, v1
	v_rcp_f32_e32 v220, v220
	v_mul_f32_e32 v218, v65, v218
	v_mul_f32_e32 v219, v66, v219
	s_mov_b64 s[6:7], 0
	v_mul_f32_e32 v1, v64, v1
	v_mul_f32_e32 v220, v67, v220
	v_cvt_pk_bf16_f32 v218, v1, v218
	v_cvt_pk_bf16_f32 v219, v219, v220
	global_store_dwordx2 v[208:209], v[218:219], off
.LBB0_1013:
	s_andn2_b64 vcc, exec, s[6:7]
	s_cbranch_vccnz .LBB0_1015
	v_lshlrev_b32_e32 v1, 16, v212
	v_and_b32_e32 v218, 0xffff0000, v212
	v_lshlrev_b32_e32 v212, 16, v213
	v_mul_f32_e32 v212, 0xbfb8aa3b, v212
	v_mul_f32_e32 v1, 0xbfb8aa3b, v1
	v_exp_f32_e32 v219, v212
	v_and_b32_e32 v212, 0xffff0000, v213
	v_exp_f32_e32 v1, v1
	v_mul_f32_e32 v218, 0xbfb8aa3b, v218
	v_mul_f32_e32 v212, 0xbfb8aa3b, v212
	v_exp_f32_e32 v218, v218
	v_exp_f32_e32 v213, v212
	v_add_f32_e32 v1, 1.0, v1
	v_rcp_f32_e32 v212, v1
	v_add_f32_e32 v1, 1.0, v218
	v_add_f32_e32 v218, 1.0, v219
	v_add_f32_e32 v213, 1.0, v213
	v_rcp_f32_e32 v218, v218
	v_rcp_f32_e32 v219, v213
	v_rcp_f32_e32 v213, v1
	v_pk_add_f32 v[214:215], v[214:215], 1.0 op_sel_hi:[1,0]
	v_pk_add_f32 v[216:217], v[216:217], 1.0 op_sel_hi:[1,0]
	v_pk_mul_f32 v[212:213], v[214:215], v[212:213]
	v_pk_mul_f32 v[216:217], v[216:217], v[218:219]
	v_pk_mul_f32 v[64:65], v[64:65], v[212:213]
	v_pk_mul_f32 v[66:67], v[66:67], v[216:217]
.LBB0_1015:
	s_waitcnt vmcnt(14)
	v_lshlrev_b32_e32 v1, 16, v210
	v_max_f32_e32 v1, 0xc2700000, v1
	v_mul_f32_e32 v1, 0xbfb8aa3b, v1
	v_exp_f32_e32 v212, v1
	v_and_b32_e32 v1, 0xffff0000, v210
	v_max_f32_e32 v1, 0xc2700000, v1
	v_mul_f32_e32 v1, 0xbfb8aa3b, v1
	v_exp_f32_e32 v213, v1
	v_lshlrev_b32_e32 v1, 16, v211
	v_max_f32_e32 v1, 0xc2700000, v1
	v_mul_f32_e32 v1, 0xbfb8aa3b, v1
	v_exp_f32_e32 v210, v1
	v_and_b32_e32 v1, 0xffff0000, v211
	v_max_f32_e32 v1, 0xc2700000, v1
	v_mul_f32_e32 v1, 0xbfb8aa3b, v1
	v_exp_f32_e32 v211, v1
	s_and_b64 vcc, exec, s[4:5]
	s_mov_b64 s[6:7], -1
	s_cbranch_vccnz .LBB0_1017
	v_add_f32_e32 v214, 1.0, v213
	v_add_f32_e32 v215, 1.0, v210
	v_add_f32_e32 v1, 1.0, v212
	v_rcp_f32_e32 v214, v214
	v_rcp_f32_e32 v215, v215
	v_add_f32_e32 v216, 1.0, v211
	v_rcp_f32_e32 v1, v1
	v_rcp_f32_e32 v216, v216
	v_mul_f32_e32 v214, v61, v214
	v_mul_f32_e32 v215, v62, v215
	s_mov_b64 s[6:7], 0
	v_mul_f32_e32 v1, v60, v1
	v_mul_f32_e32 v216, v63, v216
	v_cvt_pk_bf16_f32 v214, v1, v214
	v_cvt_pk_bf16_f32 v215, v215, v216
	global_store_dwordx2 v[208:209], v[214:215], off offset:32
.LBB0_1017:
	s_andn2_b64 vcc, exec, s[6:7]
	s_cbranch_vccnz .LBB0_1019
	v_lshlrev_b32_e32 v1, 16, v206
	v_and_b32_e32 v214, 0xffff0000, v206
	v_lshlrev_b32_e32 v206, 16, v207
	v_mul_f32_e32 v206, 0xbfb8aa3b, v206
	v_mul_f32_e32 v1, 0xbfb8aa3b, v1
	v_exp_f32_e32 v215, v206
	v_and_b32_e32 v206, 0xffff0000, v207
	v_exp_f32_e32 v1, v1
	v_mul_f32_e32 v214, 0xbfb8aa3b, v214
	v_mul_f32_e32 v206, 0xbfb8aa3b, v206
	v_exp_f32_e32 v214, v214
	v_exp_f32_e32 v207, v206
	v_add_f32_e32 v1, 1.0, v1
	v_rcp_f32_e32 v206, v1
	v_add_f32_e32 v1, 1.0, v214
	v_add_f32_e32 v214, 1.0, v215
	v_add_f32_e32 v207, 1.0, v207
	v_rcp_f32_e32 v214, v214
	v_rcp_f32_e32 v215, v207
	v_rcp_f32_e32 v207, v1
	v_pk_add_f32 v[212:213], v[212:213], 1.0 op_sel_hi:[1,0]
	v_pk_add_f32 v[210:211], v[210:211], 1.0 op_sel_hi:[1,0]
	v_pk_mul_f32 v[206:207], v[212:213], v[206:207]
	v_pk_mul_f32 v[210:211], v[210:211], v[214:215]
	v_pk_mul_f32 v[60:61], v[60:61], v[206:207]
	v_pk_mul_f32 v[62:63], v[62:63], v[210:211]
.LBB0_1019:
	s_waitcnt vmcnt(13)
	v_lshlrev_b32_e32 v1, 16, v204
	v_max_f32_e32 v1, 0xc2700000, v1
	v_mul_f32_e32 v1, 0xbfb8aa3b, v1
	v_exp_f32_e32 v206, v1
	v_and_b32_e32 v1, 0xffff0000, v204
	v_max_f32_e32 v1, 0xc2700000, v1
	v_mul_f32_e32 v1, 0xbfb8aa3b, v1
	v_exp_f32_e32 v207, v1
	v_lshlrev_b32_e32 v1, 16, v205
	v_max_f32_e32 v1, 0xc2700000, v1
	v_mul_f32_e32 v1, 0xbfb8aa3b, v1
	v_exp_f32_e32 v204, v1
	v_and_b32_e32 v1, 0xffff0000, v205
	v_max_f32_e32 v1, 0xc2700000, v1
	v_mul_f32_e32 v1, 0xbfb8aa3b, v1
	v_exp_f32_e32 v205, v1
	s_and_b64 vcc, exec, s[4:5]
	s_mov_b64 s[6:7], -1
	s_cbranch_vccnz .LBB0_1021
	v_add_f32_e32 v210, 1.0, v207
	v_add_f32_e32 v211, 1.0, v204
	v_add_f32_e32 v1, 1.0, v206
	v_rcp_f32_e32 v210, v210
	v_rcp_f32_e32 v211, v211
	v_add_f32_e32 v212, 1.0, v205
	v_rcp_f32_e32 v1, v1
	v_rcp_f32_e32 v212, v212
	v_mul_f32_e32 v210, v33, v210
	v_mul_f32_e32 v211, v34, v211
	s_mov_b64 s[6:7], 0
	v_mul_f32_e32 v1, v32, v1
	v_mul_f32_e32 v212, v35, v212
	v_cvt_pk_bf16_f32 v210, v1, v210
	v_cvt_pk_bf16_f32 v211, v211, v212
	global_store_dwordx2 v[208:209], v[210:211], off offset:256
; __device__ __forceinline__ unsigned cvt_pk_bf16(float lo, float hi) { unsigned r; asm volatile("v_cvt_pk_bf16_f32 %0, %1, %2" : "=v"(r) : "v"(lo), "v"(hi)); return r; }
;     __device__ __forceinline__ void operator()(f32x4 (&acc)[2][2][4][2], const Unit& u, int wr, int wc, int fr, int fq) const {
;     ...
;                         const unsigned long long wb = wbv[m][bj][n];
;                         f32x4 eb;
;                         eb[0] = __expf(-fmaxf(__uint_as_float((unsigned)(wb & 0xffffull) << 16), -60.f)); eb[1] = __expf(-fmaxf(__uint_as_float((unsigned)((wb >> 16) & 0xffffull) << 16), -60.f));
;                         eb[2] = __expf(-fmaxf(__uint_as_float((unsigned)((wb >> 32) & 0xffffull) << 16), -60.f)); eb[3] = __expf(-fmaxf(__uint_as_float((unsigned)((wb >> 48) & 0xffffull) << 16), -60.f));
;                         if (u.kh == 0) {
;                             const unsigned long long wa = wav[m][bj][n];
;                             f32x4 ea;
;                             ea[0] = __expf(-__uint_as_float((unsigned)(wa & 0xffffull) << 16)); ea[1] = __expf(-__uint_as_float((unsigned)((wa >> 16) & 0xffffull) << 16));
;                             ea[2] = __expf(-__uint_as_float((unsigned)((wa >> 32) & 0xffffull) << 16)); ea[3] = __expf(-__uint_as_float((unsigned)((wa >> 48) & 0xffffull) << 16));
; #pragma unroll
;                             for (int e_ = 0; e_ < 4; ++e_) acc[ai][bj][m][n][e_] *= (1.0f + eb[e_]) * __builtin_amdgcn_rcpf(1.0f + ea[e_]);
;                         } else {
;                             f32x4 o;
; #pragma unroll
;                             for (int e_ = 0; e_ < 4; ++e_) o[e_] = acc[ai][bj][m][n][e_] * __builtin_amdgcn_rcpf(1.0f + eb[e_]);
;                             *(unsigned long long*)(merged + off + bj * HALF + 16 * n) = (unsigned long long)cvt_pk_bf16(o[0], o[1]) | ((unsigned long long)cvt_pk_bf16(o[2], o[3]) << 32);
.LBB0_1021:
	s_andn2_b64 vcc, exec, s[6:7]
	s_cbranch_vccnz .LBB0_1023
	v_lshlrev_b32_e32 v1, 16, v202
	v_and_b32_e32 v210, 0xffff0000, v202
	v_lshlrev_b32_e32 v202, 16, v203
	v_mul_f32_e32 v202, 0xbfb8aa3b, v202
	v_mul_f32_e32 v1, 0xbfb8aa3b, v1
	v_exp_f32_e32 v211, v202
	v_and_b32_e32 v202, 0xffff0000, v203
	v_exp_f32_e32 v1, v1
	v_mul_f32_e32 v210, 0xbfb8aa3b, v210
	v_mul_f32_e32 v202, 0xbfb8aa3b, v202
	v_exp_f32_e32 v210, v210
	v_exp_f32_e32 v203, v202
	v_add_f32_e32 v1, 1.0, v1
	v_rcp_f32_e32 v202, v1
	v_add_f32_e32 v1, 1.0, v210
	v_add_f32_e32 v210, 1.0, v211
	v_add_f32_e32 v203, 1.0, v203
	v_rcp_f32_e32 v210, v210
	v_rcp_f32_e32 v211, v203
	v_rcp_f32_e32 v203, v1
	v_pk_add_f32 v[206:207], v[206:207], 1.0 op_sel_hi:[1,0]
	v_pk_add_f32 v[204:205], v[204:205], 1.0 op_sel_hi:[1,0]
	v_pk_mul_f32 v[202:203], v[206:207], v[202:203]
	v_pk_mul_f32 v[204:205], v[204:205], v[210:211]
	v_pk_mul_f32 v[32:33], v[32:33], v[202:203]
	v_pk_mul_f32 v[34:35], v[34:35], v[204:205]
.LBB0_1023:
	s_waitcnt vmcnt(12)
	v_lshlrev_b32_e32 v1, 16, v200
	v_max_f32_e32 v1, 0xc2700000, v1
	v_mul_f32_e32 v1, 0xbfb8aa3b, v1
	v_exp_f32_e32 v202, v1
	v_and_b32_e32 v1, 0xffff0000, v200
	v_max_f32_e32 v1, 0xc2700000, v1
	v_mul_f32_e32 v1, 0xbfb8aa3b, v1
	v_exp_f32_e32 v203, v1
	v_lshlrev_b32_e32 v1, 16, v201
	v_max_f32_e32 v1, 0xc2700000, v1
	v_mul_f32_e32 v1, 0xbfb8aa3b, v1
	v_exp_f32_e32 v200, v1
	v_and_b32_e32 v1, 0xffff0000, v201
	v_max_f32_e32 v1, 0xc2700000, v1
	v_mul_f32_e32 v1, 0xbfb8aa3b, v1
	v_exp_f32_e32 v201, v1
	s_and_b64 vcc, exec, s[4:5]
	s_mov_b64 s[6:7], -1
	s_cbranch_vccnz .LBB0_1025
	v_add_f32_e32 v204, 1.0, v203
	v_add_f32_e32 v205, 1.0, v200
	v_add_f32_e32 v1, 1.0, v202
	v_rcp_f32_e32 v204, v204
	v_rcp_f32_e32 v205, v205
	v_add_f32_e32 v206, 1.0, v201
	v_rcp_f32_e32 v1, v1
	v_rcp_f32_e32 v206, v206
	v_mul_f32_e32 v204, v29, v204
	v_mul_f32_e32 v205, v30, v205
	s_mov_b64 s[6:7], 0
	v_mul_f32_e32 v1, v28, v1
	v_mul_f32_e32 v206, v31, v206
	v_cvt_pk_bf16_f32 v204, v1, v204
	v_cvt_pk_bf16_f32 v205, v205, v206
	global_store_dwordx2 v[208:209], v[204:205], off offset:288
.LBB0_1025:
	s_andn2_b64 vcc, exec, s[6:7]
	s_cbranch_vccnz .LBB0_1027
	v_lshlrev_b32_e32 v1, 16, v198
	v_and_b32_e32 v204, 0xffff0000, v198
	v_lshlrev_b32_e32 v198, 16, v199
	v_mul_f32_e32 v198, 0xbfb8aa3b, v198
	v_mul_f32_e32 v1, 0xbfb8aa3b, v1
	v_exp_f32_e32 v205, v198
	v_and_b32_e32 v198, 0xffff0000, v199
	v_exp_f32_e32 v1, v1
	v_mul_f32_e32 v204, 0xbfb8aa3b, v204
	v_mul_f32_e32 v198, 0xbfb8aa3b, v198
	v_exp_f32_e32 v204, v204
	v_exp_f32_e32 v199, v198
	v_add_f32_e32 v1, 1.0, v1
	v_rcp_f32_e32 v198, v1
	v_add_f32_e32 v1, 1.0, v204
	v_add_f32_e32 v204, 1.0, v205
	v_add_f32_e32 v199, 1.0, v199
	v_rcp_f32_e32 v204, v204
	v_rcp_f32_e32 v205, v199
	v_rcp_f32_e32 v199, v1
	v_pk_add_f32 v[202:203], v[202:203], 1.0 op_sel_hi:[1,0]
	v_pk_add_f32 v[200:201], v[200:201], 1.0 op_sel_hi:[1,0]
	v_pk_mul_f32 v[198:199], v[202:203], v[198:199]
	v_pk_mul_f32 v[200:201], v[200:201], v[204:205]
	v_pk_mul_f32 v[28:29], v[28:29], v[198:199]
	v_pk_mul_f32 v[30:31], v[30:31], v[200:201]
.LBB0_1027:
	s_waitcnt vmcnt(11)
	v_lshlrev_b32_e32 v1, 16, v194
	v_max_f32_e32 v1, 0xc2700000, v1
	v_mul_f32_e32 v1, 0xbfb8aa3b, v1
	v_lshlrev_b64 v[200:201], 11, v[196:197]
	v_exp_f32_e32 v196, v1
	v_and_b32_e32 v1, 0xffff0000, v194
	v_max_f32_e32 v1, 0xc2700000, v1
	v_mul_f32_e32 v1, 0xbfb8aa3b, v1
	v_exp_f32_e32 v197, v1
	v_lshlrev_b32_e32 v1, 16, v195
	v_max_f32_e32 v1, 0xc2700000, v1
	v_mul_f32_e32 v1, 0xbfb8aa3b, v1
	v_exp_f32_e32 v198, v1
	v_and_b32_e32 v1, 0xffff0000, v195
	v_max_f32_e32 v1, 0xc2700000, v1
	v_mul_f32_e32 v1, 0xbfb8aa3b, v1
	v_exp_f32_e32 v199, v1
	v_lshl_add_u64 v[194:195], s[14:15], 0, v[200:201]
	s_mov_b64 s[6:7], -1
	s_and_b64 vcc, exec, s[4:5]
	v_lshl_add_u64 v[194:195], v[2:3], 1, v[194:195]
	s_cbranch_vccnz .LBB0_1029
	v_add_f32_e32 v200, 1.0, v197
	v_add_f32_e32 v201, 1.0, v198
	v_add_f32_e32 v1, 1.0, v196
	v_rcp_f32_e32 v200, v200
	v_rcp_f32_e32 v201, v201
	v_add_f32_e32 v202, 1.0, v199
	v_rcp_f32_e32 v1, v1
	v_rcp_f32_e32 v202, v202
	v_mul_f32_e32 v200, v57, v200
	v_mul_f32_e32 v201, v58, v201
	s_mov_b64 s[6:7], 0
	v_mul_f32_e32 v1, v56, v1
	v_mul_f32_e32 v202, v59, v202
	v_cvt_pk_bf16_f32 v200, v1, v200
	v_cvt_pk_bf16_f32 v201, v201, v202
	global_store_dwordx2 v[194:195], v[200:201], off
.LBB0_1029:
	s_andn2_b64 vcc, exec, s[6:7]
	s_cbranch_vccnz .LBB0_1031
	v_lshlrev_b32_e32 v1, 16, v192
	v_and_b32_e32 v200, 0xffff0000, v192
	v_lshlrev_b32_e32 v192, 16, v193
	v_mul_f32_e32 v192, 0xbfb8aa3b, v192
	v_mul_f32_e32 v1, 0xbfb8aa3b, v1
	v_exp_f32_e32 v201, v192
	v_and_b32_e32 v192, 0xffff0000, v193
	v_exp_f32_e32 v1, v1
	v_mul_f32_e32 v200, 0xbfb8aa3b, v200
	v_mul_f32_e32 v192, 0xbfb8aa3b, v192
	v_exp_f32_e32 v200, v200
	v_exp_f32_e32 v193, v192
	v_add_f32_e32 v1, 1.0, v1
	v_rcp_f32_e32 v192, v1
	v_add_f32_e32 v1, 1.0, v200
	v_add_f32_e32 v200, 1.0, v201
	v_add_f32_e32 v193, 1.0, v193
	v_rcp_f32_e32 v200, v200
	v_rcp_f32_e32 v201, v193
	v_rcp_f32_e32 v193, v1
	v_pk_add_f32 v[196:197], v[196:197], 1.0 op_sel_hi:[1,0]
	v_pk_add_f32 v[198:199], v[198:199], 1.0 op_sel_hi:[1,0]
	v_pk_mul_f32 v[192:193], v[196:197], v[192:193]
	v_pk_mul_f32 v[198:199], v[198:199], v[200:201]
	v_pk_mul_f32 v[56:57], v[56:57], v[192:193]
	v_pk_mul_f32 v[58:59], v[58:59], v[198:199]
; __device__ __forceinline__ unsigned cvt_pk_bf16(float lo, float hi) { unsigned r; asm volatile("v_cvt_pk_bf16_f32 %0, %1, %2" : "=v"(r) : "v"(lo), "v"(hi)); return r; }
;     __device__ __forceinline__ void operator()(f32x4 (&acc)[2][2][4][2], const Unit& u, int wr, int wc, int fr, int fq) const {
;     ...
;                         const unsigned long long wb = wbv[m][bj][n];
;                         f32x4 eb;
;                         eb[0] = __expf(-fmaxf(__uint_as_float((unsigned)(wb & 0xffffull) << 16), -60.f)); eb[1] = __expf(-fmaxf(__uint_as_float((unsigned)((wb >> 16) & 0xffffull) << 16), -60.f));
;                         eb[2] = __expf(-fmaxf(__uint_as_float((unsigned)((wb >> 32) & 0xffffull) << 16), -60.f)); eb[3] = __expf(-fmaxf(__uint_as_float((unsigned)((wb >> 48) & 0xffffull) << 16), -60.f));
;                         if (u.kh == 0) {
;                             const unsigned long long wa = wav[m][bj][n];
;                             f32x4 ea;
;                             ea[0] = __expf(-__uint_as_float((unsigned)(wa & 0xffffull) << 16)); ea[1] = __expf(-__uint_as_float((unsigned)((wa >> 16) & 0xffffull) << 16));
;                             ea[2] = __expf(-__uint_as_float((unsigned)((wa >> 32) & 0xffffull) << 16)); ea[3] = __expf(-__uint_as_float((unsigned)((wa >> 48) & 0xffffull) << 16));
; #pragma unroll
;                             for (int e_ = 0; e_ < 4; ++e_) acc[ai][bj][m][n][e_] *= (1.0f + eb[e_]) * __builtin_amdgcn_rcpf(1.0f + ea[e_]);
;                         } else {
;                             f32x4 o;
; #pragma unroll
;                             for (int e_ = 0; e_ < 4; ++e_) o[e_] = acc[ai][bj][m][n][e_] * __builtin_amdgcn_rcpf(1.0f + eb[e_]);
;                             *(unsigned long long*)(merged + off + bj * HALF + 16 * n) = (unsigned long long)cvt_pk_bf16(o[0], o[1]) | ((unsigned long long)cvt_pk_bf16(o[2], o[3]) << 32);
.LBB0_1031:
	s_waitcnt vmcnt(10)
	v_lshlrev_b32_e32 v1, 16, v190
	v_max_f32_e32 v1, 0xc2700000, v1
	v_mul_f32_e32 v1, 0xbfb8aa3b, v1
	v_exp_f32_e32 v192, v1
	v_and_b32_e32 v1, 0xffff0000, v190
	v_max_f32_e32 v1, 0xc2700000, v1
	v_mul_f32_e32 v1, 0xbfb8aa3b, v1
	v_exp_f32_e32 v193, v1
	v_lshlrev_b32_e32 v1, 16, v191
	v_max_f32_e32 v1, 0xc2700000, v1
	v_mul_f32_e32 v1, 0xbfb8aa3b, v1
	v_exp_f32_e32 v190, v1
	v_and_b32_e32 v1, 0xffff0000, v191
	v_max_f32_e32 v1, 0xc2700000, v1
	v_mul_f32_e32 v1, 0xbfb8aa3b, v1
	v_exp_f32_e32 v191, v1
	s_and_b64 vcc, exec, s[4:5]
	s_mov_b64 s[6:7], -1
	s_cbranch_vccnz .LBB0_1033
	v_add_f32_e32 v196, 1.0, v193
	v_add_f32_e32 v197, 1.0, v190
	v_add_f32_e32 v1, 1.0, v192
	v_rcp_f32_e32 v196, v196
	v_rcp_f32_e32 v197, v197
	v_add_f32_e32 v198, 1.0, v191
	v_rcp_f32_e32 v1, v1
	v_rcp_f32_e32 v198, v198
	v_mul_f32_e32 v196, v53, v196
	v_mul_f32_e32 v197, v54, v197
	s_mov_b64 s[6:7], 0
	v_mul_f32_e32 v1, v52, v1
	v_mul_f32_e32 v198, v55, v198
	v_cvt_pk_bf16_f32 v196, v1, v196
	v_cvt_pk_bf16_f32 v197, v197, v198
	global_store_dwordx2 v[194:195], v[196:197], off offset:32
.LBB0_1033:
	s_andn2_b64 vcc, exec, s[6:7]
	s_cbranch_vccnz .LBB0_1035
	v_lshlrev_b32_e32 v1, 16, v188
	v_and_b32_e32 v196, 0xffff0000, v188
	v_lshlrev_b32_e32 v188, 16, v189
	v_mul_f32_e32 v188, 0xbfb8aa3b, v188
	v_mul_f32_e32 v1, 0xbfb8aa3b, v1
	v_exp_f32_e32 v197, v188
	v_and_b32_e32 v188, 0xffff0000, v189
	v_exp_f32_e32 v1, v1
	v_mul_f32_e32 v196, 0xbfb8aa3b, v196
	v_mul_f32_e32 v188, 0xbfb8aa3b, v188
	v_exp_f32_e32 v196, v196
	v_exp_f32_e32 v189, v188
	v_add_f32_e32 v1, 1.0, v1
	v_rcp_f32_e32 v188, v1
	v_add_f32_e32 v1, 1.0, v196
	v_add_f32_e32 v196, 1.0, v197
	v_add_f32_e32 v189, 1.0, v189
	v_rcp_f32_e32 v196, v196
	v_rcp_f32_e32 v197, v189
	v_rcp_f32_e32 v189, v1
	v_pk_add_f32 v[192:193], v[192:193], 1.0 op_sel_hi:[1,0]
	v_pk_add_f32 v[190:191], v[190:191], 1.0 op_sel_hi:[1,0]
	v_pk_mul_f32 v[188:189], v[192:193], v[188:189]
	v_pk_mul_f32 v[190:191], v[190:191], v[196:197]
	v_pk_mul_f32 v[52:53], v[52:53], v[188:189]
	v_pk_mul_f32 v[54:55], v[54:55], v[190:191]
.LBB0_1035:
	s_waitcnt vmcnt(9)
	v_lshlrev_b32_e32 v1, 16, v186
	v_max_f32_e32 v1, 0xc2700000, v1
	v_mul_f32_e32 v1, 0xbfb8aa3b, v1
	v_exp_f32_e32 v188, v1
	v_and_b32_e32 v1, 0xffff0000, v186
	v_max_f32_e32 v1, 0xc2700000, v1
	v_mul_f32_e32 v1, 0xbfb8aa3b, v1
	v_exp_f32_e32 v189, v1
	v_lshlrev_b32_e32 v1, 16, v187
	v_max_f32_e32 v1, 0xc2700000, v1
	v_mul_f32_e32 v1, 0xbfb8aa3b, v1
	v_exp_f32_e32 v186, v1
	v_and_b32_e32 v1, 0xffff0000, v187
	v_max_f32_e32 v1, 0xc2700000, v1
	v_mul_f32_e32 v1, 0xbfb8aa3b, v1
	v_exp_f32_e32 v187, v1
	s_and_b64 vcc, exec, s[4:5]
	s_mov_b64 s[6:7], -1
	s_cbranch_vccnz .LBB0_1037
	v_add_f32_e32 v190, 1.0, v189
	v_add_f32_e32 v191, 1.0, v186
	v_add_f32_e32 v1, 1.0, v188
	v_rcp_f32_e32 v190, v190
	v_rcp_f32_e32 v191, v191
	v_add_f32_e32 v192, 1.0, v187
	v_rcp_f32_e32 v1, v1
	v_rcp_f32_e32 v192, v192
	v_mul_f32_e32 v190, v25, v190
	v_mul_f32_e32 v191, v26, v191
	s_mov_b64 s[6:7], 0
	v_mul_f32_e32 v1, v24, v1
	v_mul_f32_e32 v192, v27, v192
	v_cvt_pk_bf16_f32 v190, v1, v190
	v_cvt_pk_bf16_f32 v191, v191, v192
	global_store_dwordx2 v[194:195], v[190:191], off offset:256
.LBB0_1037:
	s_andn2_b64 vcc, exec, s[6:7]
	s_cbranch_vccnz .LBB0_1039
	v_lshlrev_b32_e32 v1, 16, v184
	v_and_b32_e32 v190, 0xffff0000, v184
	v_lshlrev_b32_e32 v184, 16, v185
	v_mul_f32_e32 v184, 0xbfb8aa3b, v184
	v_mul_f32_e32 v1, 0xbfb8aa3b, v1
	v_exp_f32_e32 v191, v184
	v_and_b32_e32 v184, 0xffff0000, v185
	v_exp_f32_e32 v1, v1
	v_mul_f32_e32 v190, 0xbfb8aa3b, v190
	v_mul_f32_e32 v184, 0xbfb8aa3b, v184
	v_exp_f32_e32 v190, v190
	v_exp_f32_e32 v185, v184
	v_add_f32_e32 v1, 1.0, v1
	v_rcp_f32_e32 v184, v1
	v_add_f32_e32 v1, 1.0, v190
	v_add_f32_e32 v190, 1.0, v191
	v_add_f32_e32 v185, 1.0, v185
	v_rcp_f32_e32 v190, v190
	v_rcp_f32_e32 v191, v185
	v_rcp_f32_e32 v185, v1
	v_pk_add_f32 v[188:189], v[188:189], 1.0 op_sel_hi:[1,0]
	v_pk_add_f32 v[186:187], v[186:187], 1.0 op_sel_hi:[1,0]
	v_pk_mul_f32 v[184:185], v[188:189], v[184:185]
	v_pk_mul_f32 v[186:187], v[186:187], v[190:191]
	v_pk_mul_f32 v[24:25], v[24:25], v[184:185]
	v_pk_mul_f32 v[26:27], v[26:27], v[186:187]
.LBB0_1039:
	s_waitcnt vmcnt(8)
	v_lshlrev_b32_e32 v1, 16, v182
	v_max_f32_e32 v1, 0xc2700000, v1
	v_mul_f32_e32 v1, 0xbfb8aa3b, v1
	v_exp_f32_e32 v184, v1
	v_and_b32_e32 v1, 0xffff0000, v182
	v_max_f32_e32 v1, 0xc2700000, v1
	v_mul_f32_e32 v1, 0xbfb8aa3b, v1
	v_exp_f32_e32 v185, v1
	v_lshlrev_b32_e32 v1, 16, v183
	v_max_f32_e32 v1, 0xc2700000, v1
	v_mul_f32_e32 v1, 0xbfb8aa3b, v1
	v_exp_f32_e32 v182, v1
	v_and_b32_e32 v1, 0xffff0000, v183
	v_max_f32_e32 v1, 0xc2700000, v1
	v_mul_f32_e32 v1, 0xbfb8aa3b, v1
	v_exp_f32_e32 v183, v1
	s_and_b64 vcc, exec, s[4:5]
	s_mov_b64 s[6:7], -1
	s_cbranch_vccnz .LBB0_1041
	v_add_f32_e32 v186, 1.0, v185
	v_add_f32_e32 v187, 1.0, v182
	v_add_f32_e32 v1, 1.0, v184
	v_rcp_f32_e32 v186, v186
	v_rcp_f32_e32 v187, v187
	v_add_f32_e32 v188, 1.0, v183
	v_rcp_f32_e32 v1, v1
	v_rcp_f32_e32 v188, v188
	v_mul_f32_e32 v186, v21, v186
	v_mul_f32_e32 v187, v22, v187
	s_mov_b64 s[6:7], 0
	v_mul_f32_e32 v1, v20, v1
	v_mul_f32_e32 v188, v23, v188
	v_cvt_pk_bf16_f32 v186, v1, v186
	v_cvt_pk_bf16_f32 v187, v187, v188
	global_store_dwordx2 v[194:195], v[186:187], off offset:288
; __device__ __forceinline__ unsigned cvt_pk_bf16(float lo, float hi) { unsigned r; asm volatile("v_cvt_pk_bf16_f32 %0, %1, %2" : "=v"(r) : "v"(lo), "v"(hi)); return r; }
;     __device__ __forceinline__ void operator()(f32x4 (&acc)[2][2][4][2], const Unit& u, int wr, int wc, int fr, int fq) const {
;     ...
;                         const unsigned long long wb = wbv[m][bj][n];
;                         f32x4 eb;
;                         eb[0] = __expf(-fmaxf(__uint_as_float((unsigned)(wb & 0xffffull) << 16), -60.f)); eb[1] = __expf(-fmaxf(__uint_as_float((unsigned)((wb >> 16) & 0xffffull) << 16), -60.f));
;                         eb[2] = __expf(-fmaxf(__uint_as_float((unsigned)((wb >> 32) & 0xffffull) << 16), -60.f)); eb[3] = __expf(-fmaxf(__uint_as_float((unsigned)((wb >> 48) & 0xffffull) << 16), -60.f));
;                         if (u.kh == 0) {
;                             const unsigned long long wa = wav[m][bj][n];
;                             f32x4 ea;
;                             ea[0] = __expf(-__uint_as_float((unsigned)(wa & 0xffffull) << 16)); ea[1] = __expf(-__uint_as_float((unsigned)((wa >> 16) & 0xffffull) << 16));
;                             ea[2] = __expf(-__uint_as_float((unsigned)((wa >> 32) & 0xffffull) << 16)); ea[3] = __expf(-__uint_as_float((unsigned)((wa >> 48) & 0xffffull) << 16));
; #pragma unroll
;                             for (int e_ = 0; e_ < 4; ++e_) acc[ai][bj][m][n][e_] *= (1.0f + eb[e_]) * __builtin_amdgcn_rcpf(1.0f + ea[e_]);
;                         } else {
;                             f32x4 o;
; #pragma unroll
;                             for (int e_ = 0; e_ < 4; ++e_) o[e_] = acc[ai][bj][m][n][e_] * __builtin_amdgcn_rcpf(1.0f + eb[e_]);
;                             *(unsigned long long*)(merged + off + bj * HALF + 16 * n) = (unsigned long long)cvt_pk_bf16(o[0], o[1]) | ((unsigned long long)cvt_pk_bf16(o[2], o[3]) << 32);
.LBB0_1041:
	s_andn2_b64 vcc, exec, s[6:7]
	s_cbranch_vccnz .LBB0_1043
	v_lshlrev_b32_e32 v1, 16, v180
	v_and_b32_e32 v186, 0xffff0000, v180
	v_lshlrev_b32_e32 v180, 16, v181
	v_mul_f32_e32 v180, 0xbfb8aa3b, v180
	v_mul_f32_e32 v1, 0xbfb8aa3b, v1
	v_exp_f32_e32 v187, v180
	v_and_b32_e32 v180, 0xffff0000, v181
	v_exp_f32_e32 v1, v1
	v_mul_f32_e32 v186, 0xbfb8aa3b, v186
	v_mul_f32_e32 v180, 0xbfb8aa3b, v180
	v_exp_f32_e32 v186, v186
	v_exp_f32_e32 v181, v180
	v_add_f32_e32 v1, 1.0, v1
	v_rcp_f32_e32 v180, v1
	v_add_f32_e32 v1, 1.0, v186
	v_add_f32_e32 v186, 1.0, v187
	v_add_f32_e32 v181, 1.0, v181
	v_rcp_f32_e32 v186, v186
	v_rcp_f32_e32 v187, v181
	v_rcp_f32_e32 v181, v1
	v_pk_add_f32 v[184:185], v[184:185], 1.0 op_sel_hi:[1,0]
	v_pk_add_f32 v[182:183], v[182:183], 1.0 op_sel_hi:[1,0]
	v_pk_mul_f32 v[180:181], v[184:185], v[180:181]
	v_pk_mul_f32 v[182:183], v[182:183], v[186:187]
	v_pk_mul_f32 v[20:21], v[20:21], v[180:181]
	v_pk_mul_f32 v[22:23], v[22:23], v[182:183]
.LBB0_1043:
	s_waitcnt vmcnt(7)
	v_lshlrev_b32_e32 v1, 16, v176
	v_max_f32_e32 v1, 0xc2700000, v1
	v_mul_f32_e32 v1, 0xbfb8aa3b, v1
	v_lshlrev_b64 v[182:183], 11, v[178:179]
	v_exp_f32_e32 v178, v1
	v_and_b32_e32 v1, 0xffff0000, v176
	v_max_f32_e32 v1, 0xc2700000, v1
	v_mul_f32_e32 v1, 0xbfb8aa3b, v1
	v_exp_f32_e32 v179, v1
	v_lshlrev_b32_e32 v1, 16, v177
	v_max_f32_e32 v1, 0xc2700000, v1
	v_mul_f32_e32 v1, 0xbfb8aa3b, v1
	v_exp_f32_e32 v180, v1
	v_and_b32_e32 v1, 0xffff0000, v177
	v_max_f32_e32 v1, 0xc2700000, v1
	v_mul_f32_e32 v1, 0xbfb8aa3b, v1
	v_exp_f32_e32 v181, v1
	v_lshl_add_u64 v[176:177], s[14:15], 0, v[182:183]
	s_mov_b64 s[6:7], -1
	s_and_b64 vcc, exec, s[4:5]
	v_lshl_add_u64 v[176:177], v[2:3], 1, v[176:177]
	s_cbranch_vccnz .LBB0_1045
	v_add_f32_e32 v182, 1.0, v179
	v_add_f32_e32 v183, 1.0, v180
	v_add_f32_e32 v1, 1.0, v178
	v_rcp_f32_e32 v182, v182
	v_rcp_f32_e32 v183, v183
	v_add_f32_e32 v184, 1.0, v181
	v_rcp_f32_e32 v1, v1
	v_rcp_f32_e32 v184, v184
	v_mul_f32_e32 v182, v49, v182
	v_mul_f32_e32 v183, v50, v183
	s_mov_b64 s[6:7], 0
	v_mul_f32_e32 v1, v48, v1
	v_mul_f32_e32 v184, v51, v184
	v_cvt_pk_bf16_f32 v182, v1, v182
	v_cvt_pk_bf16_f32 v183, v183, v184
	global_store_dwordx2 v[176:177], v[182:183], off
.LBB0_1045:
	s_andn2_b64 vcc, exec, s[6:7]
	s_cbranch_vccnz .LBB0_1047
	v_lshlrev_b32_e32 v1, 16, v174
	v_and_b32_e32 v182, 0xffff0000, v174
	v_lshlrev_b32_e32 v174, 16, v175
	v_mul_f32_e32 v174, 0xbfb8aa3b, v174
	v_mul_f32_e32 v1, 0xbfb8aa3b, v1
	v_exp_f32_e32 v183, v174
	v_and_b32_e32 v174, 0xffff0000, v175
	v_exp_f32_e32 v1, v1
	v_mul_f32_e32 v182, 0xbfb8aa3b, v182
	v_mul_f32_e32 v174, 0xbfb8aa3b, v174
	v_exp_f32_e32 v182, v182
	v_exp_f32_e32 v175, v174
	v_add_f32_e32 v1, 1.0, v1
	v_rcp_f32_e32 v174, v1
	v_add_f32_e32 v1, 1.0, v182
	v_add_f32_e32 v182, 1.0, v183
	v_add_f32_e32 v175, 1.0, v175
	v_rcp_f32_e32 v182, v182
	v_rcp_f32_e32 v183, v175
	v_rcp_f32_e32 v175, v1
	v_pk_add_f32 v[178:179], v[178:179], 1.0 op_sel_hi:[1,0]
	v_pk_add_f32 v[180:181], v[180:181], 1.0 op_sel_hi:[1,0]
	v_pk_mul_f32 v[174:175], v[178:179], v[174:175]
	v_pk_mul_f32 v[180:181], v[180:181], v[182:183]
	v_pk_mul_f32 v[48:49], v[48:49], v[174:175]
	v_pk_mul_f32 v[50:51], v[50:51], v[180:181]
.LBB0_1047:
	s_waitcnt vmcnt(6)
	v_lshlrev_b32_e32 v1, 16, v172
	v_max_f32_e32 v1, 0xc2700000, v1
	v_mul_f32_e32 v1, 0xbfb8aa3b, v1
	v_exp_f32_e32 v174, v1
	v_and_b32_e32 v1, 0xffff0000, v172
	v_max_f32_e32 v1, 0xc2700000, v1
	v_mul_f32_e32 v1, 0xbfb8aa3b, v1
	v_exp_f32_e32 v175, v1
	v_lshlrev_b32_e32 v1, 16, v173
	v_max_f32_e32 v1, 0xc2700000, v1
	v_mul_f32_e32 v1, 0xbfb8aa3b, v1
	v_exp_f32_e32 v172, v1
	v_and_b32_e32 v1, 0xffff0000, v173
	v_max_f32_e32 v1, 0xc2700000, v1
	v_mul_f32_e32 v1, 0xbfb8aa3b, v1
	v_exp_f32_e32 v173, v1
	s_and_b64 vcc, exec, s[4:5]
	s_mov_b64 s[6:7], -1
	s_cbranch_vccnz .LBB0_1049
	v_add_f32_e32 v178, 1.0, v175
	v_add_f32_e32 v179, 1.0, v172
	v_add_f32_e32 v1, 1.0, v174
	v_rcp_f32_e32 v178, v178
	v_rcp_f32_e32 v179, v179
	v_add_f32_e32 v180, 1.0, v173
	v_rcp_f32_e32 v1, v1
	v_rcp_f32_e32 v180, v180
	v_mul_f32_e32 v178, v45, v178
	v_mul_f32_e32 v179, v46, v179
	s_mov_b64 s[6:7], 0
	v_mul_f32_e32 v1, v44, v1
	v_mul_f32_e32 v180, v47, v180
	v_cvt_pk_bf16_f32 v178, v1, v178
	v_cvt_pk_bf16_f32 v179, v179, v180
	global_store_dwordx2 v[176:177], v[178:179], off offset:32
.LBB0_1049:
	s_andn2_b64 vcc, exec, s[6:7]
	s_cbranch_vccnz .LBB0_1051
	v_lshlrev_b32_e32 v1, 16, v170
	v_and_b32_e32 v178, 0xffff0000, v170
	v_lshlrev_b32_e32 v170, 16, v171
	v_mul_f32_e32 v170, 0xbfb8aa3b, v170
	v_mul_f32_e32 v1, 0xbfb8aa3b, v1
	v_exp_f32_e32 v179, v170
	v_and_b32_e32 v170, 0xffff0000, v171
	v_exp_f32_e32 v1, v1
	v_mul_f32_e32 v178, 0xbfb8aa3b, v178
	v_mul_f32_e32 v170, 0xbfb8aa3b, v170
	v_exp_f32_e32 v178, v178
	v_exp_f32_e32 v171, v170
	v_add_f32_e32 v1, 1.0, v1
	v_rcp_f32_e32 v170, v1
	v_add_f32_e32 v1, 1.0, v178
	v_add_f32_e32 v178, 1.0, v179
	v_add_f32_e32 v171, 1.0, v171
	v_rcp_f32_e32 v178, v178
	v_rcp_f32_e32 v179, v171
	v_rcp_f32_e32 v171, v1
	v_pk_add_f32 v[174:175], v[174:175], 1.0 op_sel_hi:[1,0]
	v_pk_add_f32 v[172:173], v[172:173], 1.0 op_sel_hi:[1,0]
	v_pk_mul_f32 v[170:171], v[174:175], v[170:171]
	v_pk_mul_f32 v[172:173], v[172:173], v[178:179]
	v_pk_mul_f32 v[44:45], v[44:45], v[170:171]
	v_pk_mul_f32 v[46:47], v[46:47], v[172:173]
; __device__ __forceinline__ unsigned cvt_pk_bf16(float lo, float hi) { unsigned r; asm volatile("v_cvt_pk_bf16_f32 %0, %1, %2" : "=v"(r) : "v"(lo), "v"(hi)); return r; }
;     __device__ __forceinline__ void operator()(f32x4 (&acc)[2][2][4][2], const Unit& u, int wr, int wc, int fr, int fq) const {
;     ...
;                         const unsigned long long wb = wbv[m][bj][n];
;                         f32x4 eb;
;                         eb[0] = __expf(-fmaxf(__uint_as_float((unsigned)(wb & 0xffffull) << 16), -60.f)); eb[1] = __expf(-fmaxf(__uint_as_float((unsigned)((wb >> 16) & 0xffffull) << 16), -60.f));
;                         eb[2] = __expf(-fmaxf(__uint_as_float((unsigned)((wb >> 32) & 0xffffull) << 16), -60.f)); eb[3] = __expf(-fmaxf(__uint_as_float((unsigned)((wb >> 48) & 0xffffull) << 16), -60.f));
;                         if (u.kh == 0) {
;                             const unsigned long long wa = wav[m][bj][n];
;                             f32x4 ea;
;                             ea[0] = __expf(-__uint_as_float((unsigned)(wa & 0xffffull) << 16)); ea[1] = __expf(-__uint_as_float((unsigned)((wa >> 16) & 0xffffull) << 16));
;                             ea[2] = __expf(-__uint_as_float((unsigned)((wa >> 32) & 0xffffull) << 16)); ea[3] = __expf(-__uint_as_float((unsigned)((wa >> 48) & 0xffffull) << 16));
; #pragma unroll
;                             for (int e_ = 0; e_ < 4; ++e_) acc[ai][bj][m][n][e_] *= (1.0f + eb[e_]) * __builtin_amdgcn_rcpf(1.0f + ea[e_]);
;                         } else {
;                             f32x4 o;
; #pragma unroll
;                             for (int e_ = 0; e_ < 4; ++e_) o[e_] = acc[ai][bj][m][n][e_] * __builtin_amdgcn_rcpf(1.0f + eb[e_]);
;                             *(unsigned long long*)(merged + off + bj * HALF + 16 * n) = (unsigned long long)cvt_pk_bf16(o[0], o[1]) | ((unsigned long long)cvt_pk_bf16(o[2], o[3]) << 32);
.LBB0_1051:
	s_waitcnt vmcnt(5)
	v_lshlrev_b32_e32 v1, 16, v168
	v_max_f32_e32 v1, 0xc2700000, v1
	v_mul_f32_e32 v1, 0xbfb8aa3b, v1
	v_exp_f32_e32 v170, v1
	v_and_b32_e32 v1, 0xffff0000, v168
	v_max_f32_e32 v1, 0xc2700000, v1
	v_mul_f32_e32 v1, 0xbfb8aa3b, v1
	v_exp_f32_e32 v171, v1
	v_lshlrev_b32_e32 v1, 16, v169
	v_max_f32_e32 v1, 0xc2700000, v1
	v_mul_f32_e32 v1, 0xbfb8aa3b, v1
	v_exp_f32_e32 v168, v1
	v_and_b32_e32 v1, 0xffff0000, v169
	v_max_f32_e32 v1, 0xc2700000, v1
	v_mul_f32_e32 v1, 0xbfb8aa3b, v1
	v_exp_f32_e32 v169, v1
	s_and_b64 vcc, exec, s[4:5]
	s_mov_b64 s[6:7], -1
	s_cbranch_vccnz .LBB0_1053
	v_add_f32_e32 v172, 1.0, v171
	v_add_f32_e32 v173, 1.0, v168
	v_add_f32_e32 v1, 1.0, v170
	v_rcp_f32_e32 v172, v172
	v_rcp_f32_e32 v173, v173
	v_add_f32_e32 v174, 1.0, v169
	v_rcp_f32_e32 v1, v1
	v_rcp_f32_e32 v174, v174
	v_mul_f32_e32 v172, v17, v172
	v_mul_f32_e32 v173, v18, v173
	s_mov_b64 s[6:7], 0
	v_mul_f32_e32 v1, v16, v1
	v_mul_f32_e32 v174, v19, v174
	v_cvt_pk_bf16_f32 v172, v1, v172
	v_cvt_pk_bf16_f32 v173, v173, v174
	global_store_dwordx2 v[176:177], v[172:173], off offset:256
.LBB0_1053:
	s_andn2_b64 vcc, exec, s[6:7]
	s_cbranch_vccnz .LBB0_1055
	v_lshlrev_b32_e32 v1, 16, v166
	v_and_b32_e32 v172, 0xffff0000, v166
	v_lshlrev_b32_e32 v166, 16, v167
	v_mul_f32_e32 v166, 0xbfb8aa3b, v166
	v_mul_f32_e32 v1, 0xbfb8aa3b, v1
	v_exp_f32_e32 v173, v166
	v_and_b32_e32 v166, 0xffff0000, v167
	v_exp_f32_e32 v1, v1
	v_mul_f32_e32 v172, 0xbfb8aa3b, v172
	v_mul_f32_e32 v166, 0xbfb8aa3b, v166
	v_exp_f32_e32 v172, v172
	v_exp_f32_e32 v167, v166
	v_add_f32_e32 v1, 1.0, v1
	v_rcp_f32_e32 v166, v1
	v_add_f32_e32 v1, 1.0, v172
	v_add_f32_e32 v172, 1.0, v173
	v_add_f32_e32 v167, 1.0, v167
	v_rcp_f32_e32 v172, v172
	v_rcp_f32_e32 v173, v167
	v_rcp_f32_e32 v167, v1
	v_pk_add_f32 v[170:171], v[170:171], 1.0 op_sel_hi:[1,0]
	v_pk_add_f32 v[168:169], v[168:169], 1.0 op_sel_hi:[1,0]
	v_pk_mul_f32 v[166:167], v[170:171], v[166:167]
	v_pk_mul_f32 v[168:169], v[168:169], v[172:173]
	v_pk_mul_f32 v[16:17], v[16:17], v[166:167]
	v_pk_mul_f32 v[18:19], v[18:19], v[168:169]
.LBB0_1055:
	s_waitcnt vmcnt(4)
	v_lshlrev_b32_e32 v1, 16, v164
	v_max_f32_e32 v1, 0xc2700000, v1
	v_mul_f32_e32 v1, 0xbfb8aa3b, v1
	v_exp_f32_e32 v166, v1
	v_and_b32_e32 v1, 0xffff0000, v164
	v_max_f32_e32 v1, 0xc2700000, v1
	v_mul_f32_e32 v1, 0xbfb8aa3b, v1
	v_exp_f32_e32 v167, v1
	v_lshlrev_b32_e32 v1, 16, v165
	v_max_f32_e32 v1, 0xc2700000, v1
	v_mul_f32_e32 v1, 0xbfb8aa3b, v1
	v_exp_f32_e32 v164, v1
	v_and_b32_e32 v1, 0xffff0000, v165
	v_max_f32_e32 v1, 0xc2700000, v1
	v_mul_f32_e32 v1, 0xbfb8aa3b, v1
	v_exp_f32_e32 v165, v1
	s_and_b64 vcc, exec, s[4:5]
	s_mov_b64 s[6:7], -1
	s_cbranch_vccnz .LBB0_1057
	v_add_f32_e32 v168, 1.0, v167
	v_add_f32_e32 v169, 1.0, v164
	v_add_f32_e32 v1, 1.0, v166
	v_rcp_f32_e32 v168, v168
	v_rcp_f32_e32 v169, v169
	v_add_f32_e32 v170, 1.0, v165
	v_rcp_f32_e32 v1, v1
	v_rcp_f32_e32 v170, v170
	v_mul_f32_e32 v168, v13, v168
	v_mul_f32_e32 v169, v14, v169
	s_mov_b64 s[6:7], 0
	v_mul_f32_e32 v1, v12, v1
	v_mul_f32_e32 v170, v15, v170
	v_cvt_pk_bf16_f32 v168, v1, v168
	v_cvt_pk_bf16_f32 v169, v169, v170
	global_store_dwordx2 v[176:177], v[168:169], off offset:288
.LBB0_1057:
	s_andn2_b64 vcc, exec, s[6:7]
	s_cbranch_vccnz .LBB0_1059
	v_lshlrev_b32_e32 v1, 16, v162
	v_and_b32_e32 v168, 0xffff0000, v162
	v_lshlrev_b32_e32 v162, 16, v163
	v_mul_f32_e32 v162, 0xbfb8aa3b, v162
	v_mul_f32_e32 v1, 0xbfb8aa3b, v1
	v_exp_f32_e32 v169, v162
	v_and_b32_e32 v162, 0xffff0000, v163
	v_exp_f32_e32 v1, v1
	v_mul_f32_e32 v168, 0xbfb8aa3b, v168
	v_mul_f32_e32 v162, 0xbfb8aa3b, v162
	v_exp_f32_e32 v168, v168
	v_exp_f32_e32 v163, v162
	v_add_f32_e32 v1, 1.0, v1
	v_rcp_f32_e32 v162, v1
	v_add_f32_e32 v1, 1.0, v168
	v_add_f32_e32 v168, 1.0, v169
	v_add_f32_e32 v163, 1.0, v163
	v_rcp_f32_e32 v168, v168
	v_rcp_f32_e32 v169, v163
	v_rcp_f32_e32 v163, v1
	v_pk_add_f32 v[166:167], v[166:167], 1.0 op_sel_hi:[1,0]
	v_pk_add_f32 v[164:165], v[164:165], 1.0 op_sel_hi:[1,0]
	v_pk_mul_f32 v[162:163], v[166:167], v[162:163]
	v_pk_mul_f32 v[164:165], v[164:165], v[168:169]
	v_pk_mul_f32 v[12:13], v[12:13], v[162:163]
	v_pk_mul_f32 v[14:15], v[14:15], v[164:165]
.LBB0_1059:
	s_waitcnt vmcnt(3)
	v_lshlrev_b32_e32 v1, 16, v158
	v_max_f32_e32 v1, 0xc2700000, v1
	v_mul_f32_e32 v1, 0xbfb8aa3b, v1
	v_lshlrev_b64 v[162:163], 11, v[160:161]
	v_exp_f32_e32 v160, v1
	v_and_b32_e32 v1, 0xffff0000, v158
	v_max_f32_e32 v1, 0xc2700000, v1
	v_mul_f32_e32 v1, 0xbfb8aa3b, v1
	v_exp_f32_e32 v161, v1
	v_lshlrev_b32_e32 v1, 16, v159
	v_max_f32_e32 v1, 0xc2700000, v1
	v_mul_f32_e32 v1, 0xbfb8aa3b, v1
	v_exp_f32_e32 v158, v1
	v_and_b32_e32 v1, 0xffff0000, v159
	v_max_f32_e32 v1, 0xc2700000, v1
	v_mul_f32_e32 v1, 0xbfb8aa3b, v1
	v_exp_f32_e32 v159, v1
	v_lshl_add_u64 v[162:163], s[14:15], 0, v[162:163]
	s_mov_b64 s[6:7], -1
	s_and_b64 vcc, exec, s[4:5]
	v_lshl_add_u64 v[2:3], v[2:3], 1, v[162:163]
	s_cbranch_vccnz .LBB0_1061
	v_add_f32_e32 v162, 1.0, v161
	v_add_f32_e32 v163, 1.0, v158
	v_add_f32_e32 v1, 1.0, v160
	v_rcp_f32_e32 v162, v162
	v_rcp_f32_e32 v163, v163
	v_add_f32_e32 v164, 1.0, v159
	v_rcp_f32_e32 v1, v1
	v_rcp_f32_e32 v164, v164
	v_mul_f32_e32 v162, v41, v162
	v_mul_f32_e32 v163, v42, v163
	s_mov_b64 s[6:7], 0
	v_mul_f32_e32 v1, v40, v1
	v_mul_f32_e32 v164, v43, v164
	v_cvt_pk_bf16_f32 v162, v1, v162
	v_cvt_pk_bf16_f32 v163, v163, v164
	global_store_dwordx2 v[2:3], v[162:163], off
; __device__ __forceinline__ unsigned cvt_pk_bf16(float lo, float hi) { unsigned r; asm volatile("v_cvt_pk_bf16_f32 %0, %1, %2" : "=v"(r) : "v"(lo), "v"(hi)); return r; }
;     __device__ __forceinline__ void operator()(f32x4 (&acc)[2][2][4][2], const Unit& u, int wr, int wc, int fr, int fq) const {
;     ...
;                         const unsigned long long wb = wbv[m][bj][n];
;                         f32x4 eb;
;                         eb[0] = __expf(-fmaxf(__uint_as_float((unsigned)(wb & 0xffffull) << 16), -60.f)); eb[1] = __expf(-fmaxf(__uint_as_float((unsigned)((wb >> 16) & 0xffffull) << 16), -60.f));
;                         eb[2] = __expf(-fmaxf(__uint_as_float((unsigned)((wb >> 32) & 0xffffull) << 16), -60.f)); eb[3] = __expf(-fmaxf(__uint_as_float((unsigned)((wb >> 48) & 0xffffull) << 16), -60.f));
;                         if (u.kh == 0) {
;                             const unsigned long long wa = wav[m][bj][n];
;                             f32x4 ea;
;                             ea[0] = __expf(-__uint_as_float((unsigned)(wa & 0xffffull) << 16)); ea[1] = __expf(-__uint_as_float((unsigned)((wa >> 16) & 0xffffull) << 16));
;                             ea[2] = __expf(-__uint_as_float((unsigned)((wa >> 32) & 0xffffull) << 16)); ea[3] = __expf(-__uint_as_float((unsigned)((wa >> 48) & 0xffffull) << 16));
; #pragma unroll
;                             for (int e_ = 0; e_ < 4; ++e_) acc[ai][bj][m][n][e_] *= (1.0f + eb[e_]) * __builtin_amdgcn_rcpf(1.0f + ea[e_]);
;                         } else {
;                             f32x4 o;
; #pragma unroll
;                             for (int e_ = 0; e_ < 4; ++e_) o[e_] = acc[ai][bj][m][n][e_] * __builtin_amdgcn_rcpf(1.0f + eb[e_]);
;                             *(unsigned long long*)(merged + off + bj * HALF + 16 * n) = (unsigned long long)cvt_pk_bf16(o[0], o[1]) | ((unsigned long long)cvt_pk_bf16(o[2], o[3]) << 32);
.LBB0_1061:
	s_andn2_b64 vcc, exec, s[6:7]
	s_cbranch_vccnz .LBB0_1063
	v_lshlrev_b32_e32 v1, 16, v156
	v_and_b32_e32 v162, 0xffff0000, v156
	v_lshlrev_b32_e32 v156, 16, v157
	v_mul_f32_e32 v156, 0xbfb8aa3b, v156
	v_mul_f32_e32 v1, 0xbfb8aa3b, v1
	v_exp_f32_e32 v163, v156
	v_and_b32_e32 v156, 0xffff0000, v157
	v_exp_f32_e32 v1, v1
	v_mul_f32_e32 v162, 0xbfb8aa3b, v162
	v_mul_f32_e32 v156, 0xbfb8aa3b, v156
	v_exp_f32_e32 v162, v162
	v_exp_f32_e32 v157, v156
	v_add_f32_e32 v1, 1.0, v1
	v_rcp_f32_e32 v156, v1
	v_add_f32_e32 v1, 1.0, v162
	v_add_f32_e32 v162, 1.0, v163
	v_add_f32_e32 v157, 1.0, v157
	v_rcp_f32_e32 v162, v162
	v_rcp_f32_e32 v163, v157
	v_rcp_f32_e32 v157, v1
	v_pk_add_f32 v[160:161], v[160:161], 1.0 op_sel_hi:[1,0]
	v_pk_add_f32 v[158:159], v[158:159], 1.0 op_sel_hi:[1,0]
	v_pk_mul_f32 v[156:157], v[160:161], v[156:157]
	v_pk_mul_f32 v[158:159], v[158:159], v[162:163]
	v_pk_mul_f32 v[40:41], v[40:41], v[156:157]
	v_pk_mul_f32 v[42:43], v[42:43], v[158:159]
.LBB0_1063:
	s_waitcnt vmcnt(2)
	v_lshlrev_b32_e32 v1, 16, v154
	v_max_f32_e32 v1, 0xc2700000, v1
	v_mul_f32_e32 v1, 0xbfb8aa3b, v1
	v_exp_f32_e32 v156, v1
	v_and_b32_e32 v1, 0xffff0000, v154
	v_max_f32_e32 v1, 0xc2700000, v1
	v_mul_f32_e32 v1, 0xbfb8aa3b, v1
	v_exp_f32_e32 v157, v1
	v_lshlrev_b32_e32 v1, 16, v155
	v_max_f32_e32 v1, 0xc2700000, v1
	v_mul_f32_e32 v1, 0xbfb8aa3b, v1
	v_exp_f32_e32 v154, v1
	v_and_b32_e32 v1, 0xffff0000, v155
	v_max_f32_e32 v1, 0xc2700000, v1
	v_mul_f32_e32 v1, 0xbfb8aa3b, v1
	v_exp_f32_e32 v155, v1
	s_and_b64 vcc, exec, s[4:5]
	s_mov_b64 s[6:7], -1
	s_cbranch_vccnz .LBB0_1065
	v_add_f32_e32 v158, 1.0, v157
	v_add_f32_e32 v159, 1.0, v154
	v_add_f32_e32 v1, 1.0, v156
	v_rcp_f32_e32 v158, v158
	v_rcp_f32_e32 v159, v159
	v_add_f32_e32 v160, 1.0, v155
	v_rcp_f32_e32 v1, v1
	v_rcp_f32_e32 v160, v160
	v_mul_f32_e32 v158, v37, v158
	v_mul_f32_e32 v159, v38, v159
	s_mov_b64 s[6:7], 0
	v_mul_f32_e32 v1, v36, v1
	v_mul_f32_e32 v160, v39, v160
	v_cvt_pk_bf16_f32 v158, v1, v158
	v_cvt_pk_bf16_f32 v159, v159, v160
	global_store_dwordx2 v[2:3], v[158:159], off offset:32
.LBB0_1065:
	s_andn2_b64 vcc, exec, s[6:7]
	s_cbranch_vccnz .LBB0_1067
	v_lshlrev_b32_e32 v1, 16, v152
	v_and_b32_e32 v158, 0xffff0000, v152
	v_lshlrev_b32_e32 v152, 16, v153
	v_mul_f32_e32 v152, 0xbfb8aa3b, v152
	v_mul_f32_e32 v1, 0xbfb8aa3b, v1
	v_exp_f32_e32 v159, v152
	v_and_b32_e32 v152, 0xffff0000, v153
	v_exp_f32_e32 v1, v1
	v_mul_f32_e32 v158, 0xbfb8aa3b, v158
	v_mul_f32_e32 v152, 0xbfb8aa3b, v152
	v_exp_f32_e32 v158, v158
	v_exp_f32_e32 v153, v152
	v_add_f32_e32 v1, 1.0, v1
	v_rcp_f32_e32 v152, v1
	v_add_f32_e32 v1, 1.0, v158
	v_add_f32_e32 v158, 1.0, v159
	v_add_f32_e32 v153, 1.0, v153
	v_rcp_f32_e32 v158, v158
	v_rcp_f32_e32 v159, v153
	v_rcp_f32_e32 v153, v1
	v_pk_add_f32 v[156:157], v[156:157], 1.0 op_sel_hi:[1,0]
	v_pk_add_f32 v[154:155], v[154:155], 1.0 op_sel_hi:[1,0]
	v_pk_mul_f32 v[152:153], v[156:157], v[152:153]
	v_pk_mul_f32 v[154:155], v[154:155], v[158:159]
	v_pk_mul_f32 v[36:37], v[36:37], v[152:153]
	v_pk_mul_f32 v[38:39], v[38:39], v[154:155]
.LBB0_1067:
	s_waitcnt vmcnt(1)
	v_lshlrev_b32_e32 v1, 16, v150
	v_max_f32_e32 v1, 0xc2700000, v1
	v_mul_f32_e32 v1, 0xbfb8aa3b, v1
	v_exp_f32_e32 v152, v1
	v_and_b32_e32 v1, 0xffff0000, v150
	v_max_f32_e32 v1, 0xc2700000, v1
	v_mul_f32_e32 v1, 0xbfb8aa3b, v1
	v_exp_f32_e32 v153, v1
	v_lshlrev_b32_e32 v1, 16, v151
	v_max_f32_e32 v1, 0xc2700000, v1
	v_mul_f32_e32 v1, 0xbfb8aa3b, v1
	v_exp_f32_e32 v150, v1
	v_and_b32_e32 v1, 0xffff0000, v151
	v_max_f32_e32 v1, 0xc2700000, v1
	v_mul_f32_e32 v1, 0xbfb8aa3b, v1
	v_exp_f32_e32 v151, v1
	s_and_b64 vcc, exec, s[4:5]
	s_mov_b64 s[6:7], -1
	s_cbranch_vccnz .LBB0_1069
	v_add_f32_e32 v154, 1.0, v153
	v_add_f32_e32 v155, 1.0, v150
	v_add_f32_e32 v1, 1.0, v152
	v_rcp_f32_e32 v154, v154
	v_rcp_f32_e32 v155, v155
	v_add_f32_e32 v156, 1.0, v151
	v_rcp_f32_e32 v1, v1
	v_rcp_f32_e32 v156, v156
	v_mul_f32_e32 v154, v9, v154
	v_mul_f32_e32 v155, v10, v155
	s_mov_b64 s[6:7], 0
	v_mul_f32_e32 v1, v8, v1
	v_mul_f32_e32 v156, v11, v156
	v_cvt_pk_bf16_f32 v154, v1, v154
	v_cvt_pk_bf16_f32 v155, v155, v156
	global_store_dwordx2 v[2:3], v[154:155], off offset:256
.LBB0_1069:
	s_andn2_b64 vcc, exec, s[6:7]
	s_cbranch_vccnz .LBB0_1071
	v_lshlrev_b32_e32 v1, 16, v148
	v_and_b32_e32 v154, 0xffff0000, v148
	v_lshlrev_b32_e32 v148, 16, v149
	v_mul_f32_e32 v148, 0xbfb8aa3b, v148
	v_mul_f32_e32 v1, 0xbfb8aa3b, v1
	v_exp_f32_e32 v155, v148
	v_and_b32_e32 v148, 0xffff0000, v149
	v_exp_f32_e32 v1, v1
	v_mul_f32_e32 v154, 0xbfb8aa3b, v154
	v_mul_f32_e32 v148, 0xbfb8aa3b, v148
	v_exp_f32_e32 v154, v154
	v_exp_f32_e32 v149, v148
	v_add_f32_e32 v1, 1.0, v1
	v_rcp_f32_e32 v148, v1
	v_add_f32_e32 v1, 1.0, v154
	v_add_f32_e32 v154, 1.0, v155
	v_add_f32_e32 v149, 1.0, v149
	v_rcp_f32_e32 v154, v154
	v_rcp_f32_e32 v155, v149
	v_rcp_f32_e32 v149, v1
	v_pk_add_f32 v[152:153], v[152:153], 1.0 op_sel_hi:[1,0]
	v_pk_add_f32 v[150:151], v[150:151], 1.0 op_sel_hi:[1,0]
	v_pk_mul_f32 v[148:149], v[152:153], v[148:149]
	v_pk_mul_f32 v[150:151], v[150:151], v[154:155]
	v_pk_mul_f32 v[8:9], v[8:9], v[148:149]
	v_pk_mul_f32 v[10:11], v[10:11], v[150:151]
.LBB0_1071:
	s_waitcnt vmcnt(0)
	v_lshlrev_b32_e32 v1, 16, v146
	v_max_f32_e32 v1, 0xc2700000, v1
	v_mul_f32_e32 v1, 0xbfb8aa3b, v1
	v_exp_f32_e32 v148, v1
	v_and_b32_e32 v1, 0xffff0000, v146
	v_max_f32_e32 v1, 0xc2700000, v1
	v_mul_f32_e32 v1, 0xbfb8aa3b, v1
	v_exp_f32_e32 v149, v1
	v_lshlrev_b32_e32 v1, 16, v147
	v_max_f32_e32 v1, 0xc2700000, v1
	v_mul_f32_e32 v1, 0xbfb8aa3b, v1
	v_exp_f32_e32 v146, v1
	v_and_b32_e32 v1, 0xffff0000, v147
	v_max_f32_e32 v1, 0xc2700000, v1
	v_mul_f32_e32 v1, 0xbfb8aa3b, v1
	v_exp_f32_e32 v147, v1
	s_and_b64 vcc, exec, s[4:5]
	s_mov_b64 s[4:5], -1
	s_cbranch_vccnz .LBB0_1074
	v_add_f32_e32 v150, 1.0, v149
	v_add_f32_e32 v151, 1.0, v146
	v_add_f32_e32 v1, 1.0, v148
	v_rcp_f32_e32 v150, v150
	v_rcp_f32_e32 v151, v151
	v_add_f32_e32 v152, 1.0, v147
	v_rcp_f32_e32 v1, v1
	v_rcp_f32_e32 v152, v152
	v_mul_f32_e32 v150, v5, v150
	v_mul_f32_e32 v151, v6, v151
	v_mul_f32_e32 v1, v4, v1
	v_mul_f32_e32 v152, v7, v152
	v_cvt_pk_bf16_f32 v150, v1, v150
	v_cvt_pk_bf16_f32 v151, v151, v152
	global_store_dwordx2 v[2:3], v[150:151], off offset:288
	s_cbranch_execz .LBB0_1075

;     __device__ __forceinline__ void operator()(f32x4 (&acc)[2][2][4][2], const Unit& u, int wr, int wc, int fr, int fq) const {
;     ...
;                         const unsigned long long wb = wbv[m][bj][n];
;                         f32x4 eb;
;                         eb[0] = __expf(-fmaxf(__uint_as_float((unsigned)(wb & 0xffffull) << 16), -60.f)); eb[1] = __expf(-fmaxf(__uint_as_float((unsigned)((wb >> 16) & 0xffffull) << 16), -60.f));
;                         eb[2] = __expf(-fmaxf(__uint_as_float((unsigned)((wb >> 32) & 0xffffull) << 16), -60.f)); eb[3] = __expf(-fmaxf(__uint_as_float((unsigned)((wb >> 48) & 0xffffull) << 16), -60.f));
;                         if (u.kh == 0) {
;                             const unsigned long long wa = wav[m][bj][n];
;                             f32x4 ea;
;                             ea[0] = __expf(-__uint_as_float((unsigned)(wa & 0xffffull) << 16)); ea[1] = __expf(-__uint_as_float((unsigned)((wa >> 16) & 0xffffull) << 16));
;                             ea[2] = __expf(-__uint_as_float((unsigned)((wa >> 32) & 0xffffull) << 16)); ea[3] = __expf(-__uint_as_float((unsigned)((wa >> 48) & 0xffffull) << 16));
; #pragma unroll
;                             for (int e_ = 0; e_ < 4; ++e_) acc[ai][bj][m][n][e_] *= (1.0f + eb[e_]) * __builtin_amdgcn_rcpf(1.0f + ea[e_]);
.LBB0_1075:
	v_and_b32_e32 v2, 0xffff0000, v144
	v_mul_f32_e32 v2, 0xbfb8aa3b, v2
	v_exp_f32_e32 v3, v2
	v_lshlrev_b32_e32 v2, 16, v145
	v_lshlrev_b32_e32 v1, 16, v144
	v_mul_f32_e32 v1, 0xbfb8aa3b, v1
	v_mul_f32_e32 v2, 0xbfb8aa3b, v2
	v_exp_f32_e32 v1, v1
	v_exp_f32_e32 v144, v2
	v_and_b32_e32 v2, 0xffff0000, v145
	v_mul_f32_e32 v2, 0xbfb8aa3b, v2
	v_exp_f32_e32 v145, v2
	v_add_f32_e32 v1, 1.0, v1
	v_rcp_f32_e32 v2, v1
	v_add_f32_e32 v1, 1.0, v3
	v_add_f32_e32 v3, 1.0, v144
	v_rcp_f32_e32 v144, v3
	v_add_f32_e32 v3, 1.0, v145
	v_rcp_f32_e32 v145, v3
	v_rcp_f32_e32 v3, v1
	v_pk_add_f32 v[148:149], v[148:149], 1.0 op_sel_hi:[1,0]
	v_pk_add_f32 v[146:147], v[146:147], 1.0 op_sel_hi:[1,0]
	v_pk_mul_f32 v[2:3], v[148:149], v[2:3]
	v_pk_mul_f32 v[144:145], v[146:147], v[144:145]
	v_pk_mul_f32 v[4:5], v[4:5], v[2:3]
	v_pk_mul_f32 v[6:7], v[6:7], v[144:145]
	s_andn2_b64 vcc, exec, s[0:1]
	s_mov_b64 s[0:1], -1
	s_cbranch_vccnz .LBB0_902
